# scan patch + lane-group reductions via DPP adds in gdn prep and scan (instead of LDS permutes)
# baseline (speedup 1.0000x reference)
.LBB0_314:
	v_readlane_b32 s5, v254, 54
	s_mul_i32 s2, s5, s35
	s_sub_i32 s2, s30, s2
	s_add_i32 s3, s16, s2
	s_cmp_ge_u32 s2, s5
	s_cselect_b32 s2, s3, s2
	s_sub_i32 s3, s2, s5
	s_cmp_ge_u32 s2, s5
	s_cselect_b32 s2, s3, s2
	v_readlane_b32 s3, v252, 7
	s_mul_i32 s2, s2, s3
	v_readlane_b32 s3, v252, 0
	s_add_i32 s16, s2, s3
	s_ashr_i32 s2, s16, 6
	s_mul_hi_i32 s3, s2, 0x2aaaaaab
	s_lshr_b32 s4, s3, 31
	s_lshr_b32 s3, s3, 1
	s_add_i32 s3, s3, s4
	s_mul_i32 s3, s3, 12
	s_sub_i32 s2, s2, s3
	s_and_b32 s6, s30, 1
	v_lshl_or_b32 v86, s2, 7, v175
	s_mul_i32 s3, s6, 0x8400
	v_ashrrev_i32_e32 v87, 31, v86
	v_add_u32_e32 v130, s3, v197
	v_lshl_add_u64 v[118:119], v[86:87], 2, s[22:23]
	s_mov_b64 s[2:3], 0x4800
	v_lshl_add_u64 v[90:91], v[118:119], 0, s[2:3]
	v_add_co_u32_e32 v92, vcc, s20, v118
	s_mov_b64 s[2:3], 0x9000
	s_nop 0
	v_addc_co_u32_e32 v93, vcc, 0, v119, vcc
	v_lshl_add_u64 v[94:95], v[118:119], 0, s[2:3]
	s_mov_b32 s2, 0x9000
	v_add_co_u32_e32 v96, vcc, s2, v118
	s_mov_b64 s[2:3], 0xd800
	global_load_dwordx4 v[86:89], v[118:119], off offset:16
	global_load_dwordx4 v[102:105], v[118:119], off
	global_load_dwordx4 v[106:109], v[92:93], off offset:2048
	s_nop 0
	global_load_dwordx4 v[90:93], v[90:91], off offset:16
	v_addc_co_u32_e32 v97, vcc, 0, v119, vcc
	v_lshl_add_u64 v[98:99], v[118:119], 0, s[2:3]
	s_mov_b32 s2, 0xd000
	v_add_co_u32_e32 v100, vcc, s2, v118
	global_load_dwordx4 v[110:113], v[96:97], off
	s_nop 0
	global_load_dwordx4 v[94:97], v[94:95], off offset:16
	v_addc_co_u32_e32 v101, vcc, 0, v119, vcc
	global_load_dwordx4 v[114:117], v[100:101], off offset:2048
	s_nop 0
	global_load_dwordx4 v[98:101], v[98:99], off offset:16
	s_waitcnt vmcnt(26)
	v_lshlrev_b32_e32 v154, 16, v2
	v_and_b32_e32 v155, 0xffff0000, v2
	v_lshlrev_b32_e32 v132, 16, v6
	v_and_b32_e32 v133, 0xffff0000, v6
	v_lshlrev_b32_e32 v142, 16, v10
	v_and_b32_e32 v143, 0xffff0000, v10
	s_waitcnt vmcnt(19)
	v_lshlrev_b32_e32 v120, 16, v14
	v_and_b32_e32 v121, 0xffff0000, v14
	v_lshlrev_b32_e32 v156, 16, v3
	v_and_b32_e32 v157, 0xffff0000, v3
	v_lshlrev_b32_e32 v140, 16, v7
	v_and_b32_e32 v141, 0xffff0000, v7
	v_lshlrev_b32_e32 v144, 16, v11
	v_and_b32_e32 v145, 0xffff0000, v11
	v_lshlrev_b32_e32 v164, 16, v4
	v_and_b32_e32 v165, 0xffff0000, v4
	v_lshlrev_b32_e32 v166, 16, v5
	v_and_b32_e32 v167, 0xffff0000, v5
	v_lshlrev_b32_e32 v160, 16, v9
	v_and_b32_e32 v161, 0xffff0000, v9
	s_mov_b32 s4, 0x358637bd
	s_waitcnt vmcnt(5)
	v_pk_mul_f32 v[138:139], v[106:107], v[154:155]
	s_nop 0
	v_pk_fma_f32 v[132:133], v[102:103], v[132:133], v[138:139]
	v_pk_mul_f32 v[146:147], v[108:109], v[156:157]
	s_waitcnt vmcnt(4)
	v_pk_mul_f32 v[148:149], v[90:91], v[164:165]
	v_pk_fma_f32 v[140:141], v[104:105], v[140:141], v[146:147]
	v_pk_mul_f32 v[168:169], v[92:93], v[166:167]
	v_pk_mul_f32 v[206:207], v[108:109], v[144:145]
	s_waitcnt vmcnt(3)
	v_pk_fma_f32 v[132:133], v[110:111], v[142:143], v[132:133]
	v_pk_fma_f32 v[140:141], v[112:113], v[144:145], v[140:141]
	v_pk_fma_f32 v[160:161], v[88:89], v[160:161], v[168:169]
	s_waitcnt vmcnt(1)
	v_pk_fma_f32 v[132:133], v[114:115], v[120:121], v[132:133]
	v_pk_fma_f32 v[156:157], v[104:105], v[156:157], v[206:207]
	v_pk_mul_f32 v[138:139], v[132:133], s[14:15] op_sel_hi:[1,0]
	s_nop 0
	v_exp_f32_e32 v138, v138
	v_exp_f32_e32 v139, v139
	s_nop 0
	v_pk_add_f32 v[138:139], v[138:139], 1.0 op_sel_hi:[1,0]
	s_nop 0
	v_rcp_f32_e32 v138, v138
	v_rcp_f32_e32 v139, v139
	s_nop 0
	v_pk_mul_f32 v[138:139], v[132:133], v[138:139]
	v_lshlrev_b32_e32 v132, 16, v15
	v_and_b32_e32 v133, 0xffff0000, v15
	v_pk_fma_f32 v[140:141], v[116:117], v[132:133], v[140:141]
	v_mov_b32_e32 v152, v138
	v_pk_mul_f32 v[146:147], v[140:141], s[14:15] op_sel_hi:[1,0]
	v_pk_fma_f32 v[156:157], v[112:113], v[132:133], v[156:157]
	v_exp_f32_e32 v146, v146
	v_exp_f32_e32 v147, v147
	s_nop 0
	v_pk_add_f32 v[146:147], v[146:147], 1.0 op_sel_hi:[1,0]
	s_nop 0
	v_rcp_f32_e32 v146, v146
	v_rcp_f32_e32 v147, v147
	s_nop 0
	v_pk_mul_f32 v[150:151], v[140:141], v[146:147]
	s_nop 0
	v_mov_b32_e32 v153, v150
	v_mov_b32_e32 v150, v139
	v_lshlrev_b32_e32 v140, 16, v8
	v_and_b32_e32 v141, 0xffff0000, v8
	v_pk_mul_f32 v[138:139], v[150:151], v[150:151]
	v_lshlrev_b32_e32 v146, 16, v12
	v_and_b32_e32 v147, 0xffff0000, v12
	v_pk_fma_f32 v[140:141], v[86:87], v[140:141], v[148:149]
	v_pk_fma_f32 v[162:163], v[152:153], v[152:153], v[138:139]
	v_lshlrev_b32_e32 v138, 16, v16
	v_and_b32_e32 v139, 0xffff0000, v16
	v_pk_fma_f32 v[140:141], v[94:95], v[146:147], v[140:141]
	s_waitcnt vmcnt(0)
	v_pk_fma_f32 v[140:141], v[98:99], v[138:139], v[140:141]
	s_nop 0
	v_pk_mul_f32 v[148:149], v[140:141], s[14:15] op_sel_hi:[1,0]
	s_nop 0
	v_exp_f32_e32 v148, v148
	v_exp_f32_e32 v149, v149
	s_nop 0
	v_pk_add_f32 v[148:149], v[148:149], 1.0 op_sel_hi:[1,0]
	s_nop 0
	v_rcp_f32_e32 v148, v148
	v_rcp_f32_e32 v149, v149
	s_nop 0
	v_pk_mul_f32 v[158:159], v[140:141], v[148:149]
	v_lshlrev_b32_e32 v148, 16, v13
	v_and_b32_e32 v149, 0xffff0000, v13
	v_lshlrev_b32_e32 v140, 16, v17
	v_and_b32_e32 v141, 0xffff0000, v17
	v_pk_fma_f32 v[160:161], v[96:97], v[148:149], v[160:161]
	v_mov_b32_e32 v171, v159
	v_pk_fma_f32 v[160:161], v[100:101], v[140:141], v[160:161]
	v_pk_mul_f32 v[212:213], v[92:93], v[148:149]
	v_pk_mul_f32 v[168:169], v[160:161], s[14:15] op_sel_hi:[1,0]
	v_pk_fma_f32 v[166:167], v[88:89], v[166:167], v[212:213]
	v_exp_f32_e32 v168, v168
	v_exp_f32_e32 v169, v169
	v_pk_fma_f32 v[166:167], v[96:97], v[140:141], v[166:167]
	v_pk_add_f32 v[168:169], v[168:169], 1.0 op_sel_hi:[1,0]
	s_nop 0
	v_rcp_f32_e32 v168, v168
	v_rcp_f32_e32 v169, v169
	s_nop 0
	v_pk_mul_f32 v[168:169], v[160:161], v[168:169]
	s_nop 0
	v_mov_b32_e32 v170, v169
	v_mov_b32_e32 v160, v168
	v_mov_b32_e32 v161, v158
	v_pk_mul_f32 v[170:171], v[170:171], v[170:171]
	s_nop 0
	v_pk_fma_f32 v[172:173], v[160:161], v[160:161], v[170:171]
	v_mov_b32_e32 v170, v158
	v_mov_b32_e32 v171, v168
	v_mov_b32_e32 v168, v159
	v_pk_mul_f32 v[158:159], v[106:107], v[142:143]
	v_lshlrev_b32_e32 v160, 16, v18
	v_pk_fma_f32 v[154:155], v[102:103], v[154:155], v[158:159]
	v_and_b32_e32 v161, 0xffff0000, v18
	v_pk_fma_f32 v[154:155], v[110:111], v[120:121], v[154:155]
	s_nop 0
	v_pk_fma_f32 v[154:155], v[114:115], v[160:161], v[154:155]
	s_nop 0
	v_pk_mul_f32 v[158:159], v[154:155], s[14:15] op_sel_hi:[1,0]
	s_nop 0
	v_exp_f32_e32 v158, v158
	v_exp_f32_e32 v159, v159
	s_nop 0
	v_pk_add_f32 v[158:159], v[158:159], 1.0 op_sel_hi:[1,0]
	s_nop 0
	v_rcp_f32_e32 v158, v158
	v_rcp_f32_e32 v159, v159
	s_nop 0
	v_pk_mul_f32 v[154:155], v[154:155], v[158:159]
	v_lshlrev_b32_e32 v158, 16, v19
	v_and_b32_e32 v159, 0xffff0000, v19
	v_pk_fma_f32 v[156:157], v[116:117], v[158:159], v[156:157]
	v_mov_b32_e32 v208, v154
	v_pk_mul_f32 v[206:207], v[156:157], s[14:15] op_sel_hi:[1,0]
	s_nop 0
	v_exp_f32_e32 v206, v206
	v_exp_f32_e32 v207, v207
	s_nop 0
	v_pk_add_f32 v[206:207], v[206:207], 1.0 op_sel_hi:[1,0]
	s_nop 0
	v_rcp_f32_e32 v206, v206
	v_rcp_f32_e32 v207, v207
	s_nop 0
	v_pk_mul_f32 v[206:207], v[156:157], v[206:207]
	s_nop 0
	v_mov_b32_e32 v209, v206
	v_mov_b32_e32 v206, v155
	v_pk_mul_f32 v[154:155], v[206:207], v[206:207]
	v_lshlrev_b32_e32 v156, 16, v20
	v_pk_fma_f32 v[210:211], v[208:209], v[208:209], v[154:155]
	v_pk_mul_f32 v[154:155], v[90:91], v[146:147]
	v_and_b32_e32 v157, 0xffff0000, v20
	v_pk_fma_f32 v[154:155], v[86:87], v[164:165], v[154:155]
	s_nop 0
	v_pk_fma_f32 v[154:155], v[94:95], v[138:139], v[154:155]
	s_nop 0
	v_pk_fma_f32 v[154:155], v[98:99], v[156:157], v[154:155]
	s_nop 0
	v_pk_mul_f32 v[164:165], v[154:155], s[14:15] op_sel_hi:[1,0]
	s_nop 0
	v_exp_f32_e32 v164, v164
	v_exp_f32_e32 v165, v165
	s_nop 0
	v_pk_add_f32 v[164:165], v[164:165], 1.0 op_sel_hi:[1,0]
	s_nop 0
	v_rcp_f32_e32 v164, v164
	v_rcp_f32_e32 v165, v165
	s_nop 0
	v_pk_mul_f32 v[164:165], v[154:155], v[164:165]
	v_lshlrev_b32_e32 v154, 16, v21
	v_and_b32_e32 v155, 0xffff0000, v21
	v_pk_fma_f32 v[166:167], v[100:101], v[154:155], v[166:167]
	v_mov_b32_e32 v217, v165
	v_pk_mul_f32 v[212:213], v[166:167], s[14:15] op_sel_hi:[1,0]
	s_nop 0
	v_exp_f32_e32 v212, v212
	v_exp_f32_e32 v213, v213
	s_nop 0
	v_pk_add_f32 v[212:213], v[212:213], 1.0 op_sel_hi:[1,0]
	s_nop 0
	v_rcp_f32_e32 v212, v212
	v_rcp_f32_e32 v213, v213
	s_nop 0
	v_pk_mul_f32 v[166:167], v[166:167], v[212:213]
	s_nop 0
	v_mov_b32_e32 v216, v167
	v_mov_b32_e32 v212, v166
	v_mov_b32_e32 v213, v164
	v_pk_mul_f32 v[216:217], v[216:217], v[216:217]
	s_nop 0
	v_pk_fma_f32 v[212:213], v[212:213], v[212:213], v[216:217]
	v_mov_b32_e32 v216, v210
	v_mov_b32_e32 v217, v162
	v_mov_b32_e32 v162, v211
	v_pk_add_f32 v[162:163], v[216:217], v[162:163]
	v_mov_b32_e32 v210, v213
	v_mov_b32_e32 v211, v173
	v_pk_add_f32 v[162:163], v[162:163], v[210:211]
	v_mov_b32_e32 v213, v172
	v_pk_add_f32 v[162:163], v[212:213], v[162:163]
	s_waitcnt lgkmcnt(0)
	s_nop 1
	v_add_f32_dpp v163, v163, v163 quad_perm:[1,0,3,2] row_mask:0xf bank_mask:0xf
	v_add_f32_dpp v162, v162, v162 quad_perm:[1,0,3,2] row_mask:0xf bank_mask:0xf
	s_waitcnt lgkmcnt(0)
	s_nop 1
	v_add_f32_dpp v163, v163, v163 quad_perm:[2,3,0,1] row_mask:0xf bank_mask:0xf
	v_add_f32_dpp v162, v162, v162 quad_perm:[2,3,0,1] row_mask:0xf bank_mask:0xf
	s_waitcnt lgkmcnt(0)
	s_nop 1
	v_add_f32_dpp v163, v163, v163 row_half_mirror row_mask:0xf bank_mask:0xf
	v_add_f32_dpp v162, v162, v162 row_half_mirror row_mask:0xf bank_mask:0xf
	s_waitcnt lgkmcnt(0)
	s_nop 1
	v_add_f32_dpp v163, v163, v163 row_mirror row_mask:0xf bank_mask:0xf
	v_add_f32_dpp v162, v162, v162 row_mirror row_mask:0xf bank_mask:0xf
	s_nop 0
	v_pk_add_f32 v[162:163], v[162:163], s[4:5] op_sel_hi:[1,0]
	s_nop 0
	v_mul_f32_e32 v172, 0x4b800000, v163
	v_cmp_gt_f32_e64 s[2:3], s0, v163
	v_cmp_gt_f32_e32 vcc, s0, v162
	s_nop 0
	v_cndmask_b32_e64 v163, v163, v172, s[2:3]
	v_rsq_f32_e32 v163, v163
	s_nop 0
	v_mul_f32_e32 v172, 0x45800000, v163
	v_cndmask_b32_e64 v163, v163, v172, s[2:3]
	v_mul_f32_e32 v172, 0x3db504f3, v163
	v_pk_mul_f32 v[150:151], v[150:151], v[172:173] op_sel_hi:[1,0]
	v_pk_mul_f32 v[168:169], v[168:169], v[172:173] op_sel_hi:[1,0]
	v_pk_mul_f32 v[152:153], v[152:153], v[172:173] op_sel_hi:[1,0]
	v_pk_mul_f32 v[170:171], v[170:171], v[172:173] op_sel_hi:[1,0]
	v_bfe_u32 v163, v169, 16, 1
	v_bfe_u32 v172, v168, 16, 1
	v_bfe_u32 v173, v151, 16, 1
	v_bfe_u32 v210, v150, 16, 1
	v_add3_u32 v150, v150, v210, s33
	v_add3_u32 v151, v151, v173, s33
	v_add3_u32 v168, v168, v172, s33
	v_add3_u32 v163, v169, v163, s33
	v_bfe_u32 v169, v152, 16, 1
	v_bfe_u32 v172, v153, 16, 1
	v_bfe_u32 v173, v170, 16, 1
	v_bfe_u32 v210, v171, 16, 1
	v_add3_u32 v171, v171, v210, s33
	v_add3_u32 v170, v170, v173, s33
	v_add3_u32 v153, v153, v172, s33
	v_add3_u32 v152, v152, v169, s33
	v_lshrrev_b32_e32 v169, 16, v152
	v_lshrrev_b32_e32 v172, 16, v153
	v_lshrrev_b32_e32 v152, 16, v170
	v_lshrrev_b32_e32 v153, 16, v171
	v_and_or_b32 v153, v163, s21, v153
	v_and_or_b32 v152, v168, s21, v152
	v_and_or_b32 v151, v151, s21, v172
	v_and_or_b32 v150, v150, s21, v169
	ds_write_b128 v178, v[150:153]
	v_mul_f32_e32 v150, 0x4b800000, v162
	v_cndmask_b32_e32 v150, v162, v150, vcc
	v_rsq_f32_e32 v150, v150
	v_mov_b32_e32 v168, v164
	v_mov_b32_e32 v169, v166
	v_mov_b32_e32 v166, v165
	v_mul_f32_e32 v151, 0x45800000, v150
	v_cndmask_b32_e32 v150, v150, v151, vcc
	v_mul_f32_e32 v150, 0x3db504f3, v150
	v_pk_mul_f32 v[152:153], v[208:209], v[150:151] op_sel_hi:[1,0]
	v_pk_mul_f32 v[162:163], v[206:207], v[150:151] op_sel_hi:[1,0]
	v_pk_mul_f32 v[168:169], v[168:169], v[150:151] op_sel_hi:[1,0]
	v_pk_mul_f32 v[150:151], v[166:167], v[150:151] op_sel_hi:[1,0]
	v_bfe_u32 v166, v163, 16, 1
	v_bfe_u32 v164, v151, 16, 1
	v_bfe_u32 v165, v150, 16, 1
	v_bfe_u32 v167, v162, 16, 1
	v_add3_u32 v162, v162, v167, s33
	v_add3_u32 v163, v163, v166, s33
	v_add3_u32 v150, v150, v165, s33
	v_add3_u32 v151, v151, v164, s33
	v_bfe_u32 v164, v152, 16, 1
	v_bfe_u32 v165, v153, 16, 1
	v_bfe_u32 v166, v168, 16, 1
	v_bfe_u32 v167, v169, 16, 1
	v_add3_u32 v167, v169, v167, s33
	v_add3_u32 v166, v168, v166, s33
	v_add3_u32 v153, v153, v165, s33
	v_add3_u32 v152, v152, v164, s33
	v_lshrrev_b32_e32 v164, 16, v152
	v_lshrrev_b32_e32 v165, 16, v153
	v_lshrrev_b32_e32 v152, 16, v166
	v_lshrrev_b32_e32 v153, 16, v167
	v_and_or_b32 v153, v151, s21, v153
	v_and_or_b32 v152, v150, s21, v152
	v_and_or_b32 v151, v163, s21, v165
	v_and_or_b32 v150, v162, s21, v164
	ds_write_b128 v178, v[150:153] offset:272
	v_pk_mul_f32 v[150:151], v[106:107], v[120:121]
	v_pk_mul_f32 v[106:107], v[106:107], v[160:161]
	v_lshlrev_b32_e32 v152, 16, v22
	v_and_b32_e32 v153, 0xffff0000, v22
	v_pk_fma_f32 v[142:143], v[102:103], v[142:143], v[150:151]
	v_pk_mul_f32 v[166:167], v[90:91], v[138:139]
	v_pk_fma_f32 v[102:103], v[102:103], v[120:121], v[106:107]
	v_pk_mul_f32 v[90:91], v[90:91], v[156:157]
	v_pk_fma_f32 v[142:143], v[110:111], v[160:161], v[142:143]
	v_lshlrev_b32_e32 v164, 16, v24
	v_and_b32_e32 v165, 0xffff0000, v24
	v_pk_fma_f32 v[146:147], v[86:87], v[146:147], v[166:167]
	v_pk_fma_f32 v[102:103], v[110:111], v[152:153], v[102:103]
	v_lshlrev_b32_e32 v106, 16, v26
	v_and_b32_e32 v107, 0xffff0000, v26
	v_pk_fma_f32 v[86:87], v[86:87], v[138:139], v[90:91]
	v_pk_fma_f32 v[142:143], v[114:115], v[152:153], v[142:143]
	v_pk_fma_f32 v[146:147], v[94:95], v[156:157], v[146:147]
	v_pk_fma_f32 v[102:103], v[114:115], v[106:107], v[102:103]
	v_pk_fma_f32 v[86:87], v[94:95], v[164:165], v[86:87]
	v_lshlrev_b32_e32 v90, 16, v28
	v_and_b32_e32 v91, 0xffff0000, v28
	v_pk_mul_f32 v[150:151], v[142:143], s[14:15] op_sel_hi:[1,0]
	v_pk_fma_f32 v[146:147], v[98:99], v[164:165], v[146:147]
	v_pk_mul_f32 v[106:107], v[102:103], s[14:15] op_sel_hi:[1,0]
	v_pk_fma_f32 v[86:87], v[98:99], v[90:91], v[86:87]
	v_exp_f32_e32 v150, v150
	v_exp_f32_e32 v151, v151
	v_pk_mul_f32 v[166:167], v[146:147], s[14:15] op_sel_hi:[1,0]
	v_exp_f32_e32 v106, v106
	v_exp_f32_e32 v107, v107
	v_pk_mul_f32 v[90:91], v[86:87], s[14:15] op_sel_hi:[1,0]
	v_exp_f32_e32 v166, v166
	v_exp_f32_e32 v167, v167
	v_exp_f32_e32 v90, v90
	v_exp_f32_e32 v91, v91
	v_pk_add_f32 v[150:151], v[150:151], 1.0 op_sel_hi:[1,0]
	v_pk_add_f32 v[106:107], v[106:107], 1.0 op_sel_hi:[1,0]
	v_rcp_f32_e32 v150, v150
	v_rcp_f32_e32 v151, v151
	v_pk_add_f32 v[166:167], v[166:167], 1.0 op_sel_hi:[1,0]
	v_rcp_f32_e32 v106, v106
	v_rcp_f32_e32 v107, v107
	v_pk_add_f32 v[90:91], v[90:91], 1.0 op_sel_hi:[1,0]
	v_rcp_f32_e32 v166, v166
	v_rcp_f32_e32 v167, v167
	v_rcp_f32_e32 v90, v90
	v_rcp_f32_e32 v91, v91
	v_pk_mul_f32 v[150:151], v[142:143], v[150:151]
	v_pk_mul_f32 v[142:143], v[108:109], v[132:133]
	v_pk_mul_f32 v[106:107], v[102:103], v[106:107]
	v_pk_mul_f32 v[102:103], v[108:109], v[158:159]
	v_lshlrev_b32_e32 v162, 16, v23
	v_and_b32_e32 v163, 0xffff0000, v23
	v_pk_fma_f32 v[142:143], v[104:105], v[144:145], v[142:143]
	v_pk_mul_f32 v[166:167], v[146:147], v[166:167]
	v_pk_mul_f32 v[146:147], v[92:93], v[140:141]
	v_pk_fma_f32 v[102:103], v[104:105], v[132:133], v[102:103]
	v_pk_mul_f32 v[90:91], v[86:87], v[90:91]
	v_pk_mul_f32 v[86:87], v[92:93], v[154:155]
	v_pk_fma_f32 v[142:143], v[112:113], v[158:159], v[142:143]
	v_lshlrev_b32_e32 v168, 16, v25
	v_and_b32_e32 v169, 0xffff0000, v25
	v_pk_fma_f32 v[146:147], v[88:89], v[148:149], v[146:147]
	v_pk_fma_f32 v[102:103], v[112:113], v[162:163], v[102:103]
	v_lshlrev_b32_e32 v104, 16, v27
	v_and_b32_e32 v105, 0xffff0000, v27
	v_pk_fma_f32 v[86:87], v[88:89], v[140:141], v[86:87]
	v_pk_fma_f32 v[142:143], v[116:117], v[162:163], v[142:143]
	v_pk_fma_f32 v[146:147], v[96:97], v[154:155], v[146:147]
	v_pk_fma_f32 v[102:103], v[116:117], v[104:105], v[102:103]
	v_pk_fma_f32 v[86:87], v[96:97], v[168:169], v[86:87]
	v_lshlrev_b32_e32 v88, 16, v29
	v_and_b32_e32 v89, 0xffff0000, v29
	v_pk_mul_f32 v[144:145], v[142:143], s[14:15] op_sel_hi:[1,0]
	v_pk_fma_f32 v[146:147], v[100:101], v[168:169], v[146:147]
	v_pk_mul_f32 v[104:105], v[102:103], s[14:15] op_sel_hi:[1,0]
	v_pk_fma_f32 v[86:87], v[100:101], v[88:89], v[86:87]
	v_exp_f32_e32 v144, v144
	v_exp_f32_e32 v145, v145
	v_pk_mul_f32 v[148:149], v[146:147], s[14:15] op_sel_hi:[1,0]
	v_exp_f32_e32 v104, v104
	v_exp_f32_e32 v105, v105
	v_pk_mul_f32 v[88:89], v[86:87], s[14:15] op_sel_hi:[1,0]
	v_exp_f32_e32 v148, v148
	v_exp_f32_e32 v149, v149
	v_exp_f32_e32 v88, v88
	v_exp_f32_e32 v89, v89
	v_pk_add_f32 v[144:145], v[144:145], 1.0 op_sel_hi:[1,0]
	v_pk_add_f32 v[104:105], v[104:105], 1.0 op_sel_hi:[1,0]
	v_rcp_f32_e32 v144, v144
	v_rcp_f32_e32 v145, v145
	v_pk_add_f32 v[148:149], v[148:149], 1.0 op_sel_hi:[1,0]
	v_rcp_f32_e32 v104, v104
	v_rcp_f32_e32 v105, v105
	v_pk_add_f32 v[88:89], v[88:89], 1.0 op_sel_hi:[1,0]
	v_rcp_f32_e32 v148, v148
	v_rcp_f32_e32 v149, v149
	v_rcp_f32_e32 v88, v88
	v_rcp_f32_e32 v89, v89
	v_pk_mul_f32 v[142:143], v[142:143], v[144:145]
	v_pk_mul_f32 v[102:103], v[102:103], v[104:105]
	v_mov_b32_e32 v145, v142
	v_mov_b32_e32 v142, v151
	v_pk_mul_f32 v[146:147], v[146:147], v[148:149]
	v_mov_b32_e32 v105, v102
	v_mov_b32_e32 v102, v107
	v_pk_mul_f32 v[92:93], v[86:87], v[88:89]
	v_mov_b32_e32 v144, v150
	v_pk_mul_f32 v[150:151], v[142:143], v[142:143]
	v_mov_b32_e32 v170, v147
	v_mov_b32_e32 v171, v167
	v_mov_b32_e32 v104, v106
	v_pk_mul_f32 v[106:107], v[102:103], v[102:103]
	v_mov_b32_e32 v88, v93
	v_mov_b32_e32 v89, v91
	v_pk_fma_f32 v[150:151], v[144:145], v[144:145], v[150:151]
	v_mov_b32_e32 v148, v146
	v_mov_b32_e32 v149, v166
	v_pk_mul_f32 v[170:171], v[170:171], v[170:171]
	v_pk_fma_f32 v[106:107], v[104:105], v[104:105], v[106:107]
	v_mov_b32_e32 v86, v92
	v_mov_b32_e32 v87, v90
	v_pk_mul_f32 v[88:89], v[88:89], v[88:89]
	v_pk_fma_f32 v[170:171], v[148:149], v[148:149], v[170:171]
	v_pk_fma_f32 v[86:87], v[86:87], v[86:87], v[88:89]
	v_mov_b32_e32 v88, v106
	v_mov_b32_e32 v89, v150
	v_mov_b32_e32 v150, v107
	v_pk_add_f32 v[88:89], v[88:89], v[150:151]
	v_mov_b32_e32 v94, v87
	v_mov_b32_e32 v95, v171
	v_pk_add_f32 v[88:89], v[88:89], v[94:95]
	v_mov_b32_e32 v87, v170
	v_pk_add_f32 v[86:87], v[86:87], v[88:89]
	v_mov_b32_e32 v148, v166
	v_mov_b32_e32 v149, v146
	v_mov_b32_e32 v146, v167
	v_lshlrev_b32_e32 v150, 16, v34
	s_waitcnt lgkmcnt(0)
	s_nop 1
	v_add_f32_dpp v87, v87, v87 quad_perm:[1,0,3,2] row_mask:0xf bank_mask:0xf
	v_add_f32_dpp v86, v86, v86 quad_perm:[1,0,3,2] row_mask:0xf bank_mask:0xf
	v_and_b32_e32 v151, 0xffff0000, v34
	v_lshlrev_b32_e32 v132, 16, v30
	v_and_b32_e32 v133, 0xffff0000, v30
	v_lshlrev_b32_e32 v120, 16, v42
	s_waitcnt lgkmcnt(0)
	s_nop 1
	v_add_f32_dpp v87, v87, v87 quad_perm:[2,3,0,1] row_mask:0xf bank_mask:0xf
	v_add_f32_dpp v86, v86, v86 quad_perm:[2,3,0,1] row_mask:0xf bank_mask:0xf
	v_and_b32_e32 v121, 0xffff0000, v42
	v_lshlrev_b32_e32 v152, 16, v35
	v_and_b32_e32 v153, 0xffff0000, v35
	v_lshlrev_b32_e32 v140, 16, v31
	s_waitcnt lgkmcnt(0)
	s_nop 1
	v_add_f32_dpp v87, v87, v87 row_half_mirror row_mask:0xf bank_mask:0xf
	v_add_f32_dpp v86, v86, v86 row_half_mirror row_mask:0xf bank_mask:0xf
	v_and_b32_e32 v141, 0xffff0000, v31
	v_lshlrev_b32_e32 v172, 16, v36
	v_and_b32_e32 v173, 0xffff0000, v36
	v_lshlrev_b32_e32 v206, 16, v37
	s_waitcnt lgkmcnt(0)
	s_nop 1
	v_add_f32_dpp v87, v87, v87 row_mirror row_mask:0xf bank_mask:0xf
	v_add_f32_dpp v86, v86, v86 row_mirror row_mask:0xf bank_mask:0xf
	v_and_b32_e32 v207, 0xffff0000, v37
	v_pk_add_f32 v[94:95], v[86:87], s[4:5] op_sel_hi:[1,0]
	v_lshlrev_b32_e32 v154, 16, v33
	v_mul_f32_e32 v86, 0x4b800000, v95
	v_cmp_gt_f32_e64 s[2:3], s0, v95
	v_cmp_gt_f32_e32 vcc, s0, v94
	v_and_b32_e32 v155, 0xffff0000, v33
	v_cndmask_b32_e64 v86, v95, v86, s[2:3]
	v_rsq_f32_e32 v86, v86
	s_nop 0
	v_mul_f32_e32 v87, 0x45800000, v86
	v_cndmask_b32_e64 v86, v86, v87, s[2:3]
	v_mul_f32_e32 v86, 0x3db504f3, v86
	v_pk_mul_f32 v[88:89], v[144:145], v[86:87] op_sel_hi:[1,0]
	v_pk_mul_f32 v[96:97], v[142:143], v[86:87] op_sel_hi:[1,0]
	v_pk_mul_f32 v[98:99], v[148:149], v[86:87] op_sel_hi:[1,0]
	v_pk_mul_f32 v[86:87], v[146:147], v[86:87] op_sel_hi:[1,0]
	v_bfe_u32 v101, v97, 16, 1
	v_bfe_u32 v95, v87, 16, 1
	v_bfe_u32 v100, v86, 16, 1
	v_bfe_u32 v106, v96, 16, 1
	v_add3_u32 v96, v96, v106, s33
	v_add3_u32 v97, v97, v101, s33
	v_add3_u32 v86, v86, v100, s33
	v_add3_u32 v87, v87, v95, s33
	v_bfe_u32 v95, v88, 16, 1
	v_bfe_u32 v100, v89, 16, 1
	v_bfe_u32 v101, v98, 16, 1
	v_bfe_u32 v106, v99, 16, 1
	v_add3_u32 v99, v99, v106, s33
	v_add3_u32 v98, v98, v101, s33
	v_add3_u32 v89, v89, v100, s33
	v_add3_u32 v88, v88, v95, s33
	v_lshrrev_b32_e32 v95, 16, v88
	v_lshrrev_b32_e32 v100, 16, v89
	v_lshrrev_b32_e32 v88, 16, v98
	v_lshrrev_b32_e32 v89, 16, v99
	v_and_or_b32 v89, v87, s21, v89
	v_and_or_b32 v88, v86, s21, v88
	v_and_or_b32 v87, v97, s21, v100
	v_and_or_b32 v86, v96, s21, v95
	ds_write_b128 v178, v[86:89] offset:544
	v_mul_f32_e32 v86, 0x4b800000, v94
	v_cndmask_b32_e32 v86, v94, v86, vcc
	v_rsq_f32_e32 v86, v86
	v_mov_b32_e32 v96, v90
	v_mov_b32_e32 v97, v92
	v_mov_b32_e32 v92, v91
	v_mul_f32_e32 v87, 0x45800000, v86
	v_cndmask_b32_e32 v86, v86, v87, vcc
	v_mul_f32_e32 v86, 0x3db504f3, v86
	v_pk_mul_f32 v[88:89], v[104:105], v[86:87] op_sel_hi:[1,0]
	v_pk_mul_f32 v[94:95], v[102:103], v[86:87] op_sel_hi:[1,0]
	v_pk_mul_f32 v[96:97], v[96:97], v[86:87] op_sel_hi:[1,0]
	v_pk_mul_f32 v[86:87], v[92:93], v[86:87] op_sel_hi:[1,0]
	v_bfe_u32 v92, v95, 16, 1
	v_bfe_u32 v90, v87, 16, 1
	v_bfe_u32 v91, v86, 16, 1
	v_bfe_u32 v93, v94, 16, 1
	v_add3_u32 v93, v94, v93, s33
	v_add3_u32 v92, v95, v92, s33
	v_add3_u32 v86, v86, v91, s33
	v_add3_u32 v87, v87, v90, s33
	v_bfe_u32 v90, v88, 16, 1
	v_bfe_u32 v91, v89, 16, 1
	v_bfe_u32 v94, v96, 16, 1
	v_bfe_u32 v95, v97, 16, 1
	v_add3_u32 v95, v97, v95, s33
	v_add3_u32 v94, v96, v94, s33
	v_add3_u32 v89, v89, v91, s33
	v_add3_u32 v88, v88, v90, s33
	v_lshrrev_b32_e32 v90, 16, v88
	v_lshrrev_b32_e32 v91, 16, v89
	v_lshrrev_b32_e32 v88, 16, v94
	v_lshrrev_b32_e32 v89, 16, v95
	v_and_or_b32 v89, v87, s21, v89
	v_and_or_b32 v88, v86, s21, v88
	v_and_or_b32 v87, v92, s21, v91
	v_and_or_b32 v86, v93, s21, v90
	s_mov_b64 s[2:3], 0x1800
	ds_write_b128 v178, v[86:89] offset:816
	v_lshl_add_u64 v[86:87], v[118:119], 0, s[2:3]
	s_movk_i32 s2, 0x1000
	v_add_co_u32_e32 v88, vcc, s2, v118
	s_mov_b64 s[2:3], 0x6000
	s_nop 0
	v_addc_co_u32_e32 v89, vcc, 0, v119, vcc
	v_lshl_add_u64 v[90:91], v[118:119], 0, s[2:3]
	s_movk_i32 s2, 0x6000
	v_add_co_u32_e32 v92, vcc, s2, v118
	s_mov_b64 s[2:3], 0xa800
	s_nop 0
	v_addc_co_u32_e32 v93, vcc, 0, v119, vcc
	v_lshl_add_u64 v[94:95], v[118:119], 0, s[2:3]
	s_mov_b32 s2, 0xa000
	v_add_co_u32_e32 v96, vcc, s2, v118
	s_mov_b64 s[2:3], 0xf000
	global_load_dwordx4 v[98:101], v[88:89], off offset:2048
	s_nop 0
	global_load_dwordx4 v[86:89], v[86:87], off offset:16
	s_nop 0
	global_load_dwordx4 v[102:105], v[92:93], off
	s_nop 0
	global_load_dwordx4 v[90:93], v[90:91], off offset:16
	v_addc_co_u32_e32 v97, vcc, 0, v119, vcc
	v_lshl_add_u64 v[114:115], v[118:119], 0, s[2:3]
	s_mov_b32 s2, 0xf000
	v_add_co_u32_e32 v110, vcc, s2, v118
	global_load_dwordx4 v[106:109], v[96:97], off offset:2048
	s_nop 0
	global_load_dwordx4 v[94:97], v[94:95], off offset:16
	v_addc_co_u32_e32 v111, vcc, 0, v119, vcc
	global_load_dwordx4 v[110:113], v[110:111], off
	s_nop 0
	global_load_dwordx4 v[114:117], v[114:115], off offset:16
	v_lshlrev_b32_e32 v142, 16, v38
	v_and_b32_e32 v143, 0xffff0000, v38
	v_lshlrev_b32_e32 v144, 16, v39
	v_and_b32_e32 v145, 0xffff0000, v39
	s_waitcnt vmcnt(5)
	v_pk_mul_f32 v[138:139], v[102:103], v[150:151]
	s_nop 0
	v_pk_fma_f32 v[132:133], v[98:99], v[132:133], v[138:139]
	v_pk_mul_f32 v[146:147], v[104:105], v[152:153]
	s_waitcnt vmcnt(4)
	v_pk_mul_f32 v[148:149], v[90:91], v[172:173]
	v_pk_fma_f32 v[140:141], v[100:101], v[140:141], v[146:147]
	v_pk_mul_f32 v[156:157], v[92:93], v[206:207]
	v_pk_mul_f32 v[168:169], v[104:105], v[144:145]
	s_waitcnt vmcnt(3)
	v_pk_fma_f32 v[132:133], v[106:107], v[142:143], v[132:133]
	v_pk_fma_f32 v[140:141], v[108:109], v[144:145], v[140:141]
	v_pk_fma_f32 v[154:155], v[88:89], v[154:155], v[156:157]
	s_waitcnt vmcnt(1)
	v_pk_fma_f32 v[132:133], v[110:111], v[120:121], v[132:133]
	v_pk_fma_f32 v[152:153], v[100:101], v[152:153], v[168:169]
	v_pk_mul_f32 v[138:139], v[132:133], s[14:15] op_sel_hi:[1,0]
	s_nop 0
	v_exp_f32_e32 v138, v138
	v_exp_f32_e32 v139, v139
	s_nop 0
	v_pk_add_f32 v[138:139], v[138:139], 1.0 op_sel_hi:[1,0]
	s_nop 0
	v_rcp_f32_e32 v138, v138
	v_rcp_f32_e32 v139, v139
	s_nop 0
	v_pk_mul_f32 v[138:139], v[132:133], v[138:139]
	v_lshlrev_b32_e32 v132, 16, v43
	v_and_b32_e32 v133, 0xffff0000, v43
	v_pk_fma_f32 v[140:141], v[112:113], v[132:133], v[140:141]
	v_mov_b32_e32 v160, v138
	v_pk_mul_f32 v[146:147], v[140:141], s[14:15] op_sel_hi:[1,0]
	v_pk_fma_f32 v[152:153], v[108:109], v[132:133], v[152:153]
	v_exp_f32_e32 v146, v146
	v_exp_f32_e32 v147, v147
	s_nop 0
	v_pk_add_f32 v[146:147], v[146:147], 1.0 op_sel_hi:[1,0]
	s_nop 0
	v_rcp_f32_e32 v146, v146
	v_rcp_f32_e32 v147, v147
	s_nop 0
	v_pk_mul_f32 v[158:159], v[140:141], v[146:147]
	s_nop 0
	v_mov_b32_e32 v161, v158
	v_mov_b32_e32 v158, v139
	v_lshlrev_b32_e32 v140, 16, v32
	v_and_b32_e32 v141, 0xffff0000, v32
	v_pk_mul_f32 v[138:139], v[158:159], v[158:159]
	v_lshlrev_b32_e32 v146, 16, v40
	v_and_b32_e32 v147, 0xffff0000, v40
	v_pk_fma_f32 v[140:141], v[86:87], v[140:141], v[148:149]
	v_pk_fma_f32 v[164:165], v[160:161], v[160:161], v[138:139]
	v_lshlrev_b32_e32 v138, 16, v44
	v_and_b32_e32 v139, 0xffff0000, v44
	v_pk_fma_f32 v[140:141], v[94:95], v[146:147], v[140:141]
	s_waitcnt vmcnt(0)
	v_pk_fma_f32 v[140:141], v[114:115], v[138:139], v[140:141]
	s_nop 0
	v_pk_mul_f32 v[148:149], v[140:141], s[14:15] op_sel_hi:[1,0]
	s_nop 0
	v_exp_f32_e32 v148, v148
	v_exp_f32_e32 v149, v149
	s_nop 0
	v_pk_add_f32 v[148:149], v[148:149], 1.0 op_sel_hi:[1,0]
	s_nop 0
	v_rcp_f32_e32 v148, v148
	v_rcp_f32_e32 v149, v149
	s_nop 0
	v_pk_mul_f32 v[162:163], v[140:141], v[148:149]
	v_lshlrev_b32_e32 v148, 16, v41
	v_and_b32_e32 v149, 0xffff0000, v41
	v_lshlrev_b32_e32 v140, 16, v45
	v_and_b32_e32 v141, 0xffff0000, v45
	v_pk_fma_f32 v[154:155], v[96:97], v[148:149], v[154:155]
	v_mov_b32_e32 v167, v163
	v_pk_fma_f32 v[154:155], v[116:117], v[140:141], v[154:155]
	v_pk_mul_f32 v[212:213], v[92:93], v[148:149]
	v_pk_mul_f32 v[156:157], v[154:155], s[14:15] op_sel_hi:[1,0]
	v_pk_fma_f32 v[206:207], v[88:89], v[206:207], v[212:213]
	v_exp_f32_e32 v156, v156
	v_exp_f32_e32 v157, v157
	v_pk_fma_f32 v[206:207], v[96:97], v[140:141], v[206:207]
	v_pk_add_f32 v[156:157], v[156:157], 1.0 op_sel_hi:[1,0]
	s_nop 0
	v_rcp_f32_e32 v156, v156
	v_rcp_f32_e32 v157, v157
	s_nop 0
	v_pk_mul_f32 v[154:155], v[154:155], v[156:157]
	s_nop 0
	v_mov_b32_e32 v166, v155
	v_mov_b32_e32 v156, v154
	v_mov_b32_e32 v157, v162
	v_pk_mul_f32 v[166:167], v[166:167], v[166:167]
	s_nop 0
	v_pk_fma_f32 v[208:209], v[156:157], v[156:157], v[166:167]
	v_mov_b32_e32 v166, v163
	v_mov_b32_e32 v167, v155
	v_mov_b32_e32 v163, v154
	v_pk_mul_f32 v[154:155], v[102:103], v[142:143]
	v_lshlrev_b32_e32 v156, 16, v46
	v_pk_fma_f32 v[150:151], v[98:99], v[150:151], v[154:155]
	v_and_b32_e32 v157, 0xffff0000, v46
	v_pk_fma_f32 v[150:151], v[106:107], v[120:121], v[150:151]
	s_nop 0
	v_pk_fma_f32 v[150:151], v[110:111], v[156:157], v[150:151]
	s_nop 0
	v_pk_mul_f32 v[154:155], v[150:151], s[14:15] op_sel_hi:[1,0]
	s_nop 0
	v_exp_f32_e32 v154, v154
	v_exp_f32_e32 v155, v155
	s_nop 0
	v_pk_add_f32 v[154:155], v[154:155], 1.0 op_sel_hi:[1,0]
	s_nop 0
	v_rcp_f32_e32 v154, v154
	v_rcp_f32_e32 v155, v155
	s_nop 0
	v_pk_mul_f32 v[150:151], v[150:151], v[154:155]
	v_lshlrev_b32_e32 v154, 16, v47
	v_and_b32_e32 v155, 0xffff0000, v47
	v_pk_fma_f32 v[152:153], v[112:113], v[154:155], v[152:153]
	v_mov_b32_e32 v170, v150
	v_pk_mul_f32 v[168:169], v[152:153], s[14:15] op_sel_hi:[1,0]
	s_nop 0
	v_exp_f32_e32 v168, v168
	v_exp_f32_e32 v169, v169
	s_nop 0
	v_pk_add_f32 v[168:169], v[168:169], 1.0 op_sel_hi:[1,0]
	s_nop 0
	v_rcp_f32_e32 v168, v168
	v_rcp_f32_e32 v169, v169
	s_nop 0
	v_pk_mul_f32 v[168:169], v[152:153], v[168:169]
	s_nop 0
	v_mov_b32_e32 v171, v168
	v_mov_b32_e32 v168, v151
	v_pk_mul_f32 v[150:151], v[168:169], v[168:169]
	v_lshlrev_b32_e32 v152, 16, v48
	v_pk_fma_f32 v[210:211], v[170:171], v[170:171], v[150:151]
	v_pk_mul_f32 v[150:151], v[90:91], v[146:147]
	v_and_b32_e32 v153, 0xffff0000, v48
	v_pk_fma_f32 v[150:151], v[86:87], v[172:173], v[150:151]
	s_nop 0
	v_pk_fma_f32 v[150:151], v[94:95], v[138:139], v[150:151]
	s_nop 0
	v_pk_fma_f32 v[150:151], v[114:115], v[152:153], v[150:151]
	s_nop 0
	v_pk_mul_f32 v[172:173], v[150:151], s[14:15] op_sel_hi:[1,0]
	s_nop 0
	v_exp_f32_e32 v172, v172
	v_exp_f32_e32 v173, v173
	s_nop 0
	v_pk_add_f32 v[172:173], v[172:173], 1.0 op_sel_hi:[1,0]
	s_nop 0
	v_rcp_f32_e32 v172, v172
	v_rcp_f32_e32 v173, v173
	s_nop 0
	v_pk_mul_f32 v[172:173], v[150:151], v[172:173]
	v_lshlrev_b32_e32 v150, 16, v49
	v_and_b32_e32 v151, 0xffff0000, v49
	v_pk_fma_f32 v[206:207], v[116:117], v[150:151], v[206:207]
	v_mov_b32_e32 v217, v173
	v_pk_mul_f32 v[212:213], v[206:207], s[14:15] op_sel_hi:[1,0]
	s_nop 0
	v_exp_f32_e32 v212, v212
	v_exp_f32_e32 v213, v213
	s_nop 0
	v_pk_add_f32 v[212:213], v[212:213], 1.0 op_sel_hi:[1,0]
	s_nop 0
	v_rcp_f32_e32 v212, v212
	v_rcp_f32_e32 v213, v213
	s_nop 0
	v_pk_mul_f32 v[206:207], v[206:207], v[212:213]
	s_nop 0
	v_mov_b32_e32 v216, v207
	v_mov_b32_e32 v212, v206
	v_mov_b32_e32 v213, v172
	v_pk_mul_f32 v[216:217], v[216:217], v[216:217]
	s_nop 0
	v_pk_fma_f32 v[212:213], v[212:213], v[212:213], v[216:217]
	v_mov_b32_e32 v216, v210
	v_mov_b32_e32 v217, v164
	v_mov_b32_e32 v164, v211
	v_pk_add_f32 v[164:165], v[216:217], v[164:165]
	v_mov_b32_e32 v210, v213
	v_mov_b32_e32 v211, v209
	v_pk_add_f32 v[164:165], v[164:165], v[210:211]
	v_mov_b32_e32 v213, v208
	v_pk_add_f32 v[164:165], v[212:213], v[164:165]
	s_waitcnt lgkmcnt(0)
	s_nop 1
	v_add_f32_dpp v165, v165, v165 quad_perm:[1,0,3,2] row_mask:0xf bank_mask:0xf
	v_add_f32_dpp v164, v164, v164 quad_perm:[1,0,3,2] row_mask:0xf bank_mask:0xf
	s_waitcnt lgkmcnt(0)
	s_nop 1
	v_add_f32_dpp v165, v165, v165 quad_perm:[2,3,0,1] row_mask:0xf bank_mask:0xf
	v_add_f32_dpp v164, v164, v164 quad_perm:[2,3,0,1] row_mask:0xf bank_mask:0xf
	s_waitcnt lgkmcnt(0)
	s_nop 1
	v_add_f32_dpp v165, v165, v165 row_half_mirror row_mask:0xf bank_mask:0xf
	v_add_f32_dpp v164, v164, v164 row_half_mirror row_mask:0xf bank_mask:0xf
	s_waitcnt lgkmcnt(0)
	s_nop 1
	v_add_f32_dpp v165, v165, v165 row_mirror row_mask:0xf bank_mask:0xf
	v_add_f32_dpp v164, v164, v164 row_mirror row_mask:0xf bank_mask:0xf
	s_nop 0
	v_pk_add_f32 v[164:165], v[164:165], s[4:5] op_sel_hi:[1,0]
	s_nop 0
	v_mul_f32_e32 v208, 0x4b800000, v165
	v_cmp_gt_f32_e64 s[2:3], s0, v165
	v_cmp_gt_f32_e32 vcc, s0, v164
	s_nop 0
	v_cndmask_b32_e64 v165, v165, v208, s[2:3]
	v_rsq_f32_e32 v165, v165
	s_nop 0
	v_mul_f32_e32 v208, 0x45800000, v165
	v_cndmask_b32_e64 v208, v165, v208, s[2:3]
	v_pk_mul_f32 v[158:159], v[158:159], v[208:209] op_sel_hi:[1,0]
	v_pk_mul_f32 v[166:167], v[166:167], v[208:209] op_sel_hi:[1,0]
	v_pk_mul_f32 v[160:161], v[160:161], v[208:209] op_sel_hi:[1,0]
	v_pk_mul_f32 v[162:163], v[162:163], v[208:209] op_sel_hi:[1,0]
	v_bfe_u32 v165, v167, 16, 1
	v_bfe_u32 v208, v166, 16, 1
	v_bfe_u32 v209, v159, 16, 1
	v_bfe_u32 v210, v158, 16, 1
	v_add3_u32 v158, v158, v210, s33
	v_add3_u32 v159, v159, v209, s33
	v_add3_u32 v166, v166, v208, s33
	v_add3_u32 v165, v167, v165, s33
	v_bfe_u32 v167, v160, 16, 1
	v_bfe_u32 v208, v161, 16, 1
	v_bfe_u32 v209, v162, 16, 1
	v_bfe_u32 v210, v163, 16, 1
	v_add3_u32 v163, v163, v210, s33
	v_add3_u32 v162, v162, v209, s33
	v_add3_u32 v161, v161, v208, s33
	v_add3_u32 v160, v160, v167, s33
	v_lshrrev_b32_e32 v167, 16, v160
	v_lshrrev_b32_e32 v208, 16, v161
	v_lshrrev_b32_e32 v160, 16, v162
	v_lshrrev_b32_e32 v161, 16, v163
	v_and_or_b32 v161, v165, s21, v161
	v_and_or_b32 v160, v166, s21, v160
	v_and_or_b32 v159, v159, s21, v208
	v_and_or_b32 v158, v158, s21, v167
	ds_write_b128 v183, v[158:161]
	ds_write_b128 v130, v[158:161] offset:256
	v_mul_f32_e32 v158, 0x4b800000, v164
	v_cndmask_b32_e32 v158, v164, v158, vcc
	v_rsq_f32_e32 v158, v158
	v_mov_b32_e32 v164, v173
	v_mov_b32_e32 v165, v207
	v_mov_b32_e32 v173, v206
	v_mul_f32_e32 v159, 0x45800000, v158
	v_cndmask_b32_e32 v158, v158, v159, vcc
	v_pk_mul_f32 v[160:161], v[168:169], v[158:159] op_sel_hi:[1,0]
	v_pk_mul_f32 v[164:165], v[164:165], v[158:159] op_sel_hi:[1,0]
	v_pk_mul_f32 v[162:163], v[170:171], v[158:159] op_sel_hi:[1,0]
	v_pk_mul_f32 v[158:159], v[172:173], v[158:159] op_sel_hi:[1,0]
	v_bfe_u32 v166, v165, 16, 1
	v_bfe_u32 v167, v164, 16, 1
	v_bfe_u32 v168, v161, 16, 1
	v_bfe_u32 v169, v160, 16, 1
	v_add3_u32 v169, v160, v169, s33
	v_add3_u32 v168, v161, v168, s33
	v_add3_u32 v160, v164, v167, s33
	v_add3_u32 v161, v165, v166, s33
	v_bfe_u32 v164, v162, 16, 1
	v_bfe_u32 v165, v163, 16, 1
	v_bfe_u32 v166, v158, 16, 1
	v_bfe_u32 v167, v159, 16, 1
	v_add3_u32 v159, v159, v167, s33
	v_add3_u32 v158, v158, v166, s33
	v_add3_u32 v163, v163, v165, s33
	v_add3_u32 v162, v162, v164, s33
	v_lshrrev_b32_e32 v162, 16, v162
	v_lshrrev_b32_e32 v163, 16, v163
	v_lshrrev_b32_e32 v158, 16, v158
	v_lshrrev_b32_e32 v159, 16, v159
	v_and_or_b32 v161, v161, s21, v159
	v_and_or_b32 v160, v160, s21, v158
	v_and_or_b32 v159, v168, s21, v163
	v_and_or_b32 v158, v169, s21, v162
	ds_write_b128 v183, v[158:161] offset:272
	ds_write_b128 v130, v[158:161] offset:784
	v_pk_mul_f32 v[158:159], v[102:103], v[120:121]
	v_pk_mul_f32 v[102:103], v[102:103], v[156:157]
	v_lshlrev_b32_e32 v160, 16, v50
	v_and_b32_e32 v161, 0xffff0000, v50
	v_pk_fma_f32 v[142:143], v[98:99], v[142:143], v[158:159]
	v_pk_mul_f32 v[166:167], v[90:91], v[138:139]
	v_pk_fma_f32 v[98:99], v[98:99], v[120:121], v[102:103]
	v_pk_mul_f32 v[90:91], v[90:91], v[152:153]
	v_pk_fma_f32 v[142:143], v[106:107], v[156:157], v[142:143]
	v_lshlrev_b32_e32 v164, 16, v52
	v_and_b32_e32 v165, 0xffff0000, v52
	v_pk_fma_f32 v[146:147], v[86:87], v[146:147], v[166:167]
	v_pk_fma_f32 v[98:99], v[106:107], v[160:161], v[98:99]
	v_lshlrev_b32_e32 v102, 16, v54
	v_and_b32_e32 v103, 0xffff0000, v54
	v_pk_fma_f32 v[86:87], v[86:87], v[138:139], v[90:91]
	v_pk_fma_f32 v[142:143], v[110:111], v[160:161], v[142:143]
	v_pk_fma_f32 v[98:99], v[110:111], v[102:103], v[98:99]
	v_pk_fma_f32 v[86:87], v[94:95], v[164:165], v[86:87]
	v_lshlrev_b32_e32 v90, 16, v56
	v_and_b32_e32 v91, 0xffff0000, v56
	v_pk_mul_f32 v[158:159], v[142:143], s[14:15] op_sel_hi:[1,0]
	v_pk_fma_f32 v[146:147], v[94:95], v[152:153], v[146:147]
	v_pk_mul_f32 v[102:103], v[98:99], s[14:15] op_sel_hi:[1,0]
	v_pk_fma_f32 v[86:87], v[114:115], v[90:91], v[86:87]
	v_exp_f32_e32 v158, v158
	v_exp_f32_e32 v159, v159
	v_pk_fma_f32 v[146:147], v[114:115], v[164:165], v[146:147]
	v_exp_f32_e32 v102, v102
	v_exp_f32_e32 v103, v103
	v_pk_mul_f32 v[90:91], v[86:87], s[14:15] op_sel_hi:[1,0]
	v_pk_mul_f32 v[166:167], v[146:147], s[14:15] op_sel_hi:[1,0]
	v_exp_f32_e32 v90, v90
	v_exp_f32_e32 v91, v91
	v_exp_f32_e32 v166, v166
	v_exp_f32_e32 v167, v167
	v_pk_add_f32 v[158:159], v[158:159], 1.0 op_sel_hi:[1,0]
	v_pk_add_f32 v[102:103], v[102:103], 1.0 op_sel_hi:[1,0]
	v_rcp_f32_e32 v158, v158
	v_rcp_f32_e32 v159, v159
	v_rcp_f32_e32 v102, v102
	v_rcp_f32_e32 v103, v103
	v_pk_add_f32 v[90:91], v[90:91], 1.0 op_sel_hi:[1,0]
	v_pk_add_f32 v[166:167], v[166:167], 1.0 op_sel_hi:[1,0]
	v_rcp_f32_e32 v90, v90
	v_rcp_f32_e32 v91, v91
	v_rcp_f32_e32 v166, v166
	v_rcp_f32_e32 v167, v167
	v_pk_mul_f32 v[158:159], v[142:143], v[158:159]
	v_pk_mul_f32 v[142:143], v[104:105], v[132:133]
	v_pk_mul_f32 v[102:103], v[98:99], v[102:103]
	v_pk_mul_f32 v[98:99], v[104:105], v[154:155]
	v_lshlrev_b32_e32 v162, 16, v51
	v_and_b32_e32 v163, 0xffff0000, v51
	v_pk_fma_f32 v[142:143], v[100:101], v[144:145], v[142:143]
	v_pk_mul_f32 v[168:169], v[92:93], v[140:141]
	v_pk_fma_f32 v[98:99], v[100:101], v[132:133], v[98:99]
	v_pk_mul_f32 v[90:91], v[86:87], v[90:91]
	v_pk_mul_f32 v[86:87], v[92:93], v[150:151]
	v_pk_fma_f32 v[142:143], v[108:109], v[154:155], v[142:143]
	v_pk_mul_f32 v[146:147], v[146:147], v[166:167]
	v_lshlrev_b32_e32 v166, 16, v53
	v_and_b32_e32 v167, 0xffff0000, v53
	v_pk_fma_f32 v[148:149], v[88:89], v[148:149], v[168:169]
	v_pk_fma_f32 v[98:99], v[108:109], v[162:163], v[98:99]
	v_lshlrev_b32_e32 v100, 16, v55
	v_and_b32_e32 v101, 0xffff0000, v55
	v_pk_fma_f32 v[86:87], v[88:89], v[140:141], v[86:87]
	v_pk_fma_f32 v[142:143], v[112:113], v[162:163], v[142:143]
	v_pk_fma_f32 v[148:149], v[96:97], v[150:151], v[148:149]
	v_pk_fma_f32 v[98:99], v[112:113], v[100:101], v[98:99]
	v_pk_fma_f32 v[86:87], v[96:97], v[166:167], v[86:87]
	v_lshlrev_b32_e32 v88, 16, v57
	v_and_b32_e32 v89, 0xffff0000, v57
	v_pk_mul_f32 v[144:145], v[142:143], s[14:15] op_sel_hi:[1,0]
	v_pk_fma_f32 v[148:149], v[116:117], v[166:167], v[148:149]
	v_pk_mul_f32 v[100:101], v[98:99], s[14:15] op_sel_hi:[1,0]
	v_pk_fma_f32 v[86:87], v[116:117], v[88:89], v[86:87]
	v_exp_f32_e32 v144, v144
	v_exp_f32_e32 v145, v145
	v_pk_mul_f32 v[168:169], v[148:149], s[14:15] op_sel_hi:[1,0]
	v_exp_f32_e32 v100, v100
	v_exp_f32_e32 v101, v101
	v_pk_mul_f32 v[88:89], v[86:87], s[14:15] op_sel_hi:[1,0]
	v_exp_f32_e32 v168, v168
	v_exp_f32_e32 v169, v169
	v_exp_f32_e32 v88, v88
	v_exp_f32_e32 v89, v89
	v_pk_add_f32 v[144:145], v[144:145], 1.0 op_sel_hi:[1,0]
	v_pk_add_f32 v[100:101], v[100:101], 1.0 op_sel_hi:[1,0]
	v_rcp_f32_e32 v144, v144
	v_rcp_f32_e32 v145, v145
	v_pk_add_f32 v[168:169], v[168:169], 1.0 op_sel_hi:[1,0]
	v_rcp_f32_e32 v100, v100
	v_rcp_f32_e32 v101, v101
	v_pk_add_f32 v[88:89], v[88:89], 1.0 op_sel_hi:[1,0]
	v_rcp_f32_e32 v168, v168
	v_rcp_f32_e32 v169, v169
	v_rcp_f32_e32 v88, v88
	v_rcp_f32_e32 v89, v89
	v_pk_mul_f32 v[142:143], v[142:143], v[144:145]
	v_pk_mul_f32 v[98:99], v[98:99], v[100:101]
	v_mov_b32_e32 v145, v142
	v_mov_b32_e32 v142, v159
	v_pk_mul_f32 v[168:169], v[148:149], v[168:169]
	v_mov_b32_e32 v101, v98
	v_mov_b32_e32 v98, v103
	v_pk_mul_f32 v[92:93], v[86:87], v[88:89]
	v_mov_b32_e32 v144, v158
	v_pk_mul_f32 v[158:159], v[142:143], v[142:143]
	v_mov_b32_e32 v170, v169
	v_mov_b32_e32 v171, v147
	v_mov_b32_e32 v100, v102
	v_pk_mul_f32 v[102:103], v[98:99], v[98:99]
	v_mov_b32_e32 v88, v93
	v_mov_b32_e32 v89, v91
	v_pk_fma_f32 v[158:159], v[144:145], v[144:145], v[158:159]
	v_mov_b32_e32 v148, v168
	v_mov_b32_e32 v149, v146
	v_pk_mul_f32 v[170:171], v[170:171], v[170:171]
	v_pk_fma_f32 v[102:103], v[100:101], v[100:101], v[102:103]
	v_mov_b32_e32 v86, v92
	v_mov_b32_e32 v87, v90
	v_pk_mul_f32 v[88:89], v[88:89], v[88:89]
	v_pk_fma_f32 v[170:171], v[148:149], v[148:149], v[170:171]
	v_pk_fma_f32 v[86:87], v[86:87], v[86:87], v[88:89]
	v_mov_b32_e32 v88, v102
	v_mov_b32_e32 v89, v158
	v_mov_b32_e32 v158, v103
	v_pk_add_f32 v[88:89], v[88:89], v[158:159]
	v_mov_b32_e32 v94, v87
	v_mov_b32_e32 v95, v171
	v_pk_add_f32 v[88:89], v[88:89], v[94:95]
	v_mov_b32_e32 v87, v170
	v_pk_add_f32 v[86:87], v[86:87], v[88:89]
	v_mov_b32_e32 v148, v147
	v_mov_b32_e32 v149, v169
	v_mov_b32_e32 v147, v168
	v_lshlrev_b32_e32 v154, 16, v62
	s_waitcnt lgkmcnt(0)
	s_nop 1
	v_add_f32_dpp v87, v87, v87 quad_perm:[1,0,3,2] row_mask:0xf bank_mask:0xf
	v_add_f32_dpp v86, v86, v86 quad_perm:[1,0,3,2] row_mask:0xf bank_mask:0xf
	v_and_b32_e32 v155, 0xffff0000, v62
	v_lshlrev_b32_e32 v120, 16, v58
	v_and_b32_e32 v121, 0xffff0000, v58
	v_lshlrev_b32_e32 v140, 16, v66
	s_waitcnt lgkmcnt(0)
	s_nop 1
	v_add_f32_dpp v87, v87, v87 quad_perm:[2,3,0,1] row_mask:0xf bank_mask:0xf
	v_add_f32_dpp v86, v86, v86 quad_perm:[2,3,0,1] row_mask:0xf bank_mask:0xf
	v_and_b32_e32 v141, 0xffff0000, v66
	v_lshlrev_b32_e32 v156, 16, v63
	v_and_b32_e32 v157, 0xffff0000, v63
	v_lshlrev_b32_e32 v160, 16, v64
	s_waitcnt lgkmcnt(0)
	s_nop 1
	v_add_f32_dpp v87, v87, v87 row_half_mirror row_mask:0xf bank_mask:0xf
	v_add_f32_dpp v86, v86, v86 row_half_mirror row_mask:0xf bank_mask:0xf
	v_and_b32_e32 v161, 0xffff0000, v64
	v_lshlrev_b32_e32 v150, 16, v68
	v_and_b32_e32 v151, 0xffff0000, v68
	v_lshlrev_b32_e32 v166, 16, v65
	s_waitcnt lgkmcnt(0)
	s_nop 1
	v_add_f32_dpp v87, v87, v87 row_mirror row_mask:0xf bank_mask:0xf
	v_add_f32_dpp v86, v86, v86 row_mirror row_mask:0xf bank_mask:0xf
	v_and_b32_e32 v167, 0xffff0000, v65
	v_pk_add_f32 v[94:95], v[86:87], s[4:5] op_sel_hi:[1,0]
	v_lshlrev_b32_e32 v168, 16, v61
	v_mul_f32_e32 v86, 0x4b800000, v95
	v_cmp_gt_f32_e64 s[2:3], s0, v95
	v_cmp_gt_f32_e32 vcc, s0, v94
	v_and_b32_e32 v169, 0xffff0000, v61
	v_cndmask_b32_e64 v86, v95, v86, s[2:3]
	v_rsq_f32_e32 v86, v86
	s_nop 0
	v_mul_f32_e32 v87, 0x45800000, v86
	v_cndmask_b32_e64 v86, v86, v87, s[2:3]
	v_pk_mul_f32 v[88:89], v[142:143], v[86:87] op_sel_hi:[1,0]
	v_pk_mul_f32 v[102:103], v[148:149], v[86:87] op_sel_hi:[1,0]
	v_pk_mul_f32 v[96:97], v[144:145], v[86:87] op_sel_hi:[1,0]
	v_pk_mul_f32 v[86:87], v[146:147], v[86:87] op_sel_hi:[1,0]
	v_bfe_u32 v95, v103, 16, 1
	v_bfe_u32 v104, v102, 16, 1
	v_bfe_u32 v105, v89, 16, 1
	v_bfe_u32 v106, v88, 16, 1
	v_add3_u32 v106, v88, v106, s33
	v_add3_u32 v105, v89, v105, s33
	v_add3_u32 v88, v102, v104, s33
	v_add3_u32 v89, v103, v95, s33
	v_bfe_u32 v95, v96, 16, 1
	v_bfe_u32 v102, v97, 16, 1
	v_bfe_u32 v103, v86, 16, 1
	v_bfe_u32 v104, v87, 16, 1
	v_add3_u32 v87, v87, v104, s33
	v_add3_u32 v86, v86, v103, s33
	v_add3_u32 v97, v97, v102, s33
	v_add3_u32 v95, v96, v95, s33
	v_lshrrev_b32_e32 v95, 16, v95
	v_lshrrev_b32_e32 v96, 16, v97
	v_lshrrev_b32_e32 v86, 16, v86
	v_lshrrev_b32_e32 v87, 16, v87
	v_and_or_b32 v89, v89, s21, v87
	v_and_or_b32 v88, v88, s21, v86
	v_and_or_b32 v87, v105, s21, v96
	v_and_or_b32 v86, v106, s21, v95
	ds_write_b128 v183, v[86:89] offset:544
	ds_write_b128 v130, v[86:89] offset:1312
	v_mul_f32_e32 v86, 0x4b800000, v94
	v_cndmask_b32_e32 v86, v94, v86, vcc
	v_rsq_f32_e32 v86, v86
	v_mov_b32_e32 v96, v91
	v_mov_b32_e32 v97, v93
	v_mov_b32_e32 v91, v92
	v_mul_f32_e32 v87, 0x45800000, v86
	v_cndmask_b32_e32 v86, v86, v87, vcc
	v_pk_mul_f32 v[88:89], v[98:99], v[86:87] op_sel_hi:[1,0]
	v_pk_mul_f32 v[96:97], v[96:97], v[86:87] op_sel_hi:[1,0]
	v_pk_mul_f32 v[94:95], v[100:101], v[86:87] op_sel_hi:[1,0]
	v_pk_mul_f32 v[86:87], v[90:91], v[86:87] op_sel_hi:[1,0]
	v_bfe_u32 v90, v97, 16, 1
	v_bfe_u32 v91, v96, 16, 1
	v_bfe_u32 v92, v89, 16, 1
	v_bfe_u32 v93, v88, 16, 1
	v_add3_u32 v93, v88, v93, s33
	v_add3_u32 v92, v89, v92, s33
	v_add3_u32 v88, v96, v91, s33
	v_add3_u32 v89, v97, v90, s33
	v_bfe_u32 v90, v94, 16, 1
	v_bfe_u32 v91, v95, 16, 1
	v_bfe_u32 v96, v86, 16, 1
	v_bfe_u32 v97, v87, 16, 1
	v_add3_u32 v87, v87, v97, s33
	v_add3_u32 v86, v86, v96, s33
	v_add3_u32 v91, v95, v91, s33
	v_add3_u32 v90, v94, v90, s33
	v_lshrrev_b32_e32 v90, 16, v90
	v_lshrrev_b32_e32 v91, 16, v91
	v_lshrrev_b32_e32 v86, 16, v86
	v_lshrrev_b32_e32 v87, 16, v87
	v_and_or_b32 v89, v89, s21, v87
	v_and_or_b32 v88, v88, s21, v86
	v_and_or_b32 v87, v92, s21, v91
	v_and_or_b32 v86, v93, s21, v90
	s_mov_b64 s[2:3], 0x3000
	ds_write_b128 v183, v[86:89] offset:816
	ds_write_b128 v130, v[86:89] offset:1840
	v_lshl_add_u64 v[86:87], v[118:119], 0, s[2:3]
	s_movk_i32 s2, 0x3000
	v_add_co_u32_e32 v88, vcc, s2, v118
	s_mov_b64 s[2:3], 0x7800
	s_nop 0
	v_addc_co_u32_e32 v89, vcc, 0, v119, vcc
	v_lshl_add_u64 v[90:91], v[118:119], 0, s[2:3]
	s_movk_i32 s2, 0x7000
	v_add_co_u32_e32 v92, vcc, s2, v118
	s_mov_b64 s[2:3], 0xc000
	s_nop 0
	v_addc_co_u32_e32 v93, vcc, 0, v119, vcc
	v_lshl_add_u64 v[98:99], v[118:119], 0, s[2:3]
	s_mov_b32 s2, 0xc000
	v_add_co_u32_e32 v100, vcc, s2, v118
	s_mov_b64 s[2:3], 0x10800
	global_load_dwordx4 v[94:97], v[88:89], off
	s_nop 0
	global_load_dwordx4 v[86:89], v[86:87], off offset:16
	s_nop 0
	global_load_dwordx4 v[102:105], v[92:93], off offset:2048
	s_nop 0
	global_load_dwordx4 v[90:93], v[90:91], off offset:16
	v_addc_co_u32_e32 v101, vcc, 0, v119, vcc
	v_lshl_add_u64 v[114:115], v[118:119], 0, s[2:3]
	s_mov_b32 s2, 0x10000
	v_add_co_u32_e32 v110, vcc, s2, v118
	global_load_dwordx4 v[106:109], v[100:101], off
	s_nop 0
	global_load_dwordx4 v[98:101], v[98:99], off offset:16
	v_addc_co_u32_e32 v111, vcc, 0, v119, vcc
	global_load_dwordx4 v[110:113], v[110:111], off offset:2048
	s_nop 0
	global_load_dwordx4 v[114:117], v[114:115], off offset:16
	v_lshlrev_b32_e32 v118, 16, v70
	v_and_b32_e32 v119, 0xffff0000, v70
	v_lshlrev_b32_e32 v142, 16, v67
	v_and_b32_e32 v143, 0xffff0000, v67
	s_waitcnt vmcnt(5)
	v_pk_mul_f32 v[132:133], v[102:103], v[154:155]
	s_nop 0
	v_pk_fma_f32 v[120:121], v[94:95], v[120:121], v[132:133]
	v_lshlrev_b32_e32 v132, 16, v59
	v_and_b32_e32 v133, 0xffff0000, v59
	v_pk_mul_f32 v[138:139], v[104:105], v[156:157]
	s_waitcnt vmcnt(4)
	v_pk_mul_f32 v[152:153], v[90:91], v[160:161]
	v_pk_fma_f32 v[132:133], v[96:97], v[132:133], v[138:139]
	s_waitcnt vmcnt(3)
	v_pk_fma_f32 v[120:121], v[106:107], v[140:141], v[120:121]
	v_pk_fma_f32 v[132:133], v[108:109], v[142:143], v[132:133]
	v_lshlrev_b32_e32 v138, 16, v60
	s_waitcnt vmcnt(1)
	v_pk_fma_f32 v[144:145], v[110:111], v[118:119], v[120:121]
	v_and_b32_e32 v139, 0xffff0000, v60
	v_pk_mul_f32 v[120:121], v[144:145], s[14:15] op_sel_hi:[1,0]
	v_pk_fma_f32 v[138:139], v[86:87], v[138:139], v[152:153]
	v_exp_f32_e32 v120, v120
	v_exp_f32_e32 v121, v121
	v_pk_fma_f32 v[138:139], v[98:99], v[150:151], v[138:139]
	v_pk_mul_f32 v[170:171], v[92:93], v[166:167]
	v_lshlrev_b32_e32 v152, 16, v69
	v_pk_add_f32 v[120:121], v[120:121], 1.0 op_sel_hi:[1,0]
	v_and_b32_e32 v153, 0xffff0000, v69
	v_rcp_f32_e32 v146, v120
	v_rcp_f32_e32 v147, v121
	v_lshlrev_b32_e32 v120, 16, v71
	v_and_b32_e32 v121, 0xffff0000, v71
	v_pk_fma_f32 v[148:149], v[112:113], v[120:121], v[132:133]
	v_pk_fma_f32 v[168:169], v[88:89], v[168:169], v[170:171]
	v_pk_mul_f32 v[132:133], v[148:149], s[14:15] op_sel_hi:[1,0]
	v_pk_fma_f32 v[168:169], v[100:101], v[152:153], v[168:169]
	v_exp_f32_e32 v132, v132
	v_exp_f32_e32 v133, v133
	v_pk_mul_f32 v[144:145], v[144:145], v[146:147]
	v_pk_add_f32 v[132:133], v[132:133], 1.0 op_sel_hi:[1,0]
	s_nop 0
	v_rcp_f32_e32 v158, v132
	v_rcp_f32_e32 v159, v133
	v_lshlrev_b32_e32 v132, 16, v72
	v_and_b32_e32 v133, 0xffff0000, v72
	s_waitcnt vmcnt(0)
	v_pk_fma_f32 v[162:163], v[114:115], v[132:133], v[138:139]
	v_pk_mul_f32 v[146:147], v[148:149], v[158:159]
	v_pk_mul_f32 v[138:139], v[162:163], s[14:15] op_sel_hi:[1,0]
	s_nop 0
	v_exp_f32_e32 v138, v138
	v_exp_f32_e32 v139, v139
	s_nop 0
	v_pk_add_f32 v[138:139], v[138:139], 1.0 op_sel_hi:[1,0]
	s_nop 0
	v_rcp_f32_e32 v164, v138
	v_rcp_f32_e32 v165, v139
	v_lshlrev_b32_e32 v138, 16, v73
	v_and_b32_e32 v139, 0xffff0000, v73
	v_pk_fma_f32 v[168:169], v[116:117], v[138:139], v[168:169]
	v_pk_mul_f32 v[148:149], v[162:163], v[164:165]
	v_pk_mul_f32 v[170:171], v[168:169], s[14:15] op_sel_hi:[1,0]
	v_bfe_u32 v162, v144, 16, 1
	v_exp_f32_e32 v170, v170
	v_exp_f32_e32 v171, v171
	v_add3_u32 v144, v144, v162, s33
	v_bfe_u32 v162, v145, 16, 1
	v_lshrrev_b32_e32 v144, 16, v144
	v_add3_u32 v145, v145, v162, s33
	v_pk_add_f32 v[170:171], v[170:171], 1.0 op_sel_hi:[1,0]
	v_and_or_b32 v144, v145, s21, v144
	v_bfe_u32 v145, v146, 16, 1
	v_rcp_f32_e32 v170, v170
	v_rcp_f32_e32 v171, v171
	v_add3_u32 v145, v146, v145, s33
	v_bfe_u32 v146, v147, 16, 1
	v_lshrrev_b32_e32 v145, 16, v145
	v_add3_u32 v146, v147, v146, s33
	v_and_or_b32 v145, v146, s21, v145
	v_bfe_u32 v146, v148, 16, 1
	v_add3_u32 v146, v148, v146, s33
	v_bfe_u32 v147, v149, 16, 1
	v_pk_mul_f32 v[158:159], v[168:169], v[170:171]
	v_lshrrev_b32_e32 v146, 16, v146
	v_add3_u32 v147, v149, v147, s33
	v_and_or_b32 v146, v147, s21, v146
	v_bfe_u32 v147, v158, 16, 1
	v_add3_u32 v147, v158, v147, s33
	v_bfe_u32 v148, v159, 16, 1
	v_lshrrev_b32_e32 v147, 16, v147
	v_add3_u32 v148, v159, v148, s33
	v_and_or_b32 v147, v148, s21, v147
	ds_write_b128 v130, v[144:147]
	v_pk_mul_f32 v[144:145], v[102:103], v[140:141]
	v_lshlrev_b32_e32 v148, 16, v74
	v_pk_fma_f32 v[144:145], v[94:95], v[154:155], v[144:145]
	v_and_b32_e32 v149, 0xffff0000, v74
	v_pk_fma_f32 v[144:145], v[106:107], v[118:119], v[144:145]
	v_lshlrev_b32_e32 v146, 16, v75
	v_pk_fma_f32 v[154:155], v[110:111], v[148:149], v[144:145]
	v_and_b32_e32 v147, 0xffff0000, v75
	v_pk_mul_f32 v[144:145], v[154:155], s[14:15] op_sel_hi:[1,0]
	v_pk_mul_f32 v[164:165], v[90:91], v[150:151]
	v_exp_f32_e32 v144, v144
	v_exp_f32_e32 v145, v145
	v_pk_mul_f32 v[170:171], v[92:93], v[152:153]
	v_pk_fma_f32 v[160:161], v[86:87], v[160:161], v[164:165]
	v_pk_fma_f32 v[166:167], v[88:89], v[166:167], v[170:171]
	v_pk_add_f32 v[144:145], v[144:145], 1.0 op_sel_hi:[1,0]
	v_pk_fma_f32 v[160:161], v[98:99], v[132:133], v[160:161]
	v_rcp_f32_e32 v158, v144
	v_rcp_f32_e32 v159, v145
	v_pk_mul_f32 v[144:145], v[104:105], v[142:143]
	v_lshlrev_b32_e32 v168, 16, v77
	v_pk_fma_f32 v[144:145], v[96:97], v[156:157], v[144:145]
	v_and_b32_e32 v169, 0xffff0000, v77
	v_pk_fma_f32 v[144:145], v[108:109], v[120:121], v[144:145]
	v_pk_fma_f32 v[166:167], v[100:101], v[138:139], v[166:167]
	v_pk_fma_f32 v[156:157], v[112:113], v[146:147], v[144:145]
	v_pk_fma_f32 v[166:167], v[116:117], v[168:169], v[166:167]
	v_pk_mul_f32 v[144:145], v[156:157], s[14:15] op_sel_hi:[1,0]
	v_pk_mul_f32 v[170:171], v[166:167], s[14:15] op_sel_hi:[1,0]
	v_exp_f32_e32 v144, v144
	v_exp_f32_e32 v145, v145
	v_exp_f32_e32 v170, v170
	v_exp_f32_e32 v171, v171
	v_pk_mul_f32 v[154:155], v[154:155], v[158:159]
	v_pk_add_f32 v[144:145], v[144:145], 1.0 op_sel_hi:[1,0]
	v_pk_add_f32 v[170:171], v[170:171], 1.0 op_sel_hi:[1,0]
	v_rcp_f32_e32 v162, v144
	v_rcp_f32_e32 v163, v145
	v_lshlrev_b32_e32 v144, 16, v76
	v_and_b32_e32 v145, 0xffff0000, v76
	v_pk_fma_f32 v[160:161], v[114:115], v[144:145], v[160:161]
	v_rcp_f32_e32 v170, v170
	v_pk_mul_f32 v[164:165], v[160:161], s[14:15] op_sel_hi:[1,0]
	v_rcp_f32_e32 v171, v171
	v_exp_f32_e32 v164, v164
	v_exp_f32_e32 v165, v165
	v_pk_mul_f32 v[156:157], v[156:157], v[162:163]
	v_bfe_u32 v162, v154, 16, 1
	v_add3_u32 v154, v154, v162, s33
	v_pk_add_f32 v[164:165], v[164:165], 1.0 op_sel_hi:[1,0]
	v_bfe_u32 v162, v155, 16, 1
	v_rcp_f32_e32 v164, v164
	v_rcp_f32_e32 v165, v165
	v_lshrrev_b32_e32 v154, 16, v154
	v_add3_u32 v155, v155, v162, s33
	v_and_or_b32 v154, v155, s21, v154
	v_pk_mul_f32 v[158:159], v[160:161], v[164:165]
	v_pk_mul_f32 v[160:161], v[166:167], v[170:171]
	v_pk_mul_f32 v[170:171], v[92:93], v[138:139]
	v_pk_mul_f32 v[92:93], v[92:93], v[168:169]
	v_lshlrev_b32_e32 v166, 16, v81
	v_and_b32_e32 v167, 0xffff0000, v81
	v_pk_fma_f32 v[152:153], v[88:89], v[152:153], v[170:171]
	v_pk_fma_f32 v[88:89], v[88:89], v[138:139], v[92:93]
	v_lshlrev_b32_e32 v92, 16, v85
	v_pk_fma_f32 v[88:89], v[100:101], v[166:167], v[88:89]
	v_and_b32_e32 v93, 0xffff0000, v85
	v_pk_fma_f32 v[88:89], v[116:117], v[92:93], v[88:89]
	v_bfe_u32 v155, v156, 16, 1
	v_pk_mul_f32 v[92:93], v[88:89], s[14:15] op_sel_hi:[1,0]
	v_add3_u32 v155, v156, v155, s33
	v_exp_f32_e32 v92, v92
	v_exp_f32_e32 v93, v93
	v_bfe_u32 v156, v157, 16, 1
	v_lshrrev_b32_e32 v155, 16, v155
	v_add3_u32 v156, v157, v156, s33
	v_and_or_b32 v155, v156, s21, v155
	v_bfe_u32 v156, v158, 16, 1
	v_add3_u32 v156, v158, v156, s33
	v_bfe_u32 v157, v159, 16, 1
	v_pk_add_f32 v[92:93], v[92:93], 1.0 op_sel_hi:[1,0]
	v_lshrrev_b32_e32 v156, 16, v156
	v_add3_u32 v157, v159, v157, s33
	v_rcp_f32_e32 v92, v92
	v_rcp_f32_e32 v93, v93
	v_and_or_b32 v156, v157, s21, v156
	v_bfe_u32 v157, v160, 16, 1
	v_add3_u32 v157, v160, v157, s33
	v_bfe_u32 v158, v161, 16, 1
	v_lshrrev_b32_e32 v157, 16, v157
	v_add3_u32 v158, v161, v158, s33
	v_and_or_b32 v157, v158, s21, v157
	v_pk_mul_f32 v[92:93], v[88:89], v[92:93]
	v_pk_mul_f32 v[88:89], v[102:103], v[148:149]
	ds_write_b128 v130, v[154:157] offset:528
	v_lshlrev_b32_e32 v154, 16, v78
	v_and_b32_e32 v155, 0xffff0000, v78
	v_pk_mul_f32 v[156:157], v[102:103], v[118:119]
	v_pk_fma_f32 v[88:89], v[94:95], v[118:119], v[88:89]
	v_pk_fma_f32 v[140:141], v[94:95], v[140:141], v[156:157]
	v_pk_fma_f32 v[88:89], v[106:107], v[154:155], v[88:89]
	v_lshlrev_b32_e32 v94, 16, v82
	v_and_b32_e32 v95, 0xffff0000, v82
	v_pk_fma_f32 v[88:89], v[110:111], v[94:95], v[88:89]
	v_pk_mul_f32 v[164:165], v[90:91], v[132:133]
	v_pk_mul_f32 v[94:95], v[88:89], s[14:15] op_sel_hi:[1,0]
	v_pk_mul_f32 v[90:91], v[90:91], v[144:145]
	v_exp_f32_e32 v94, v94
	v_exp_f32_e32 v95, v95
	v_pk_fma_f32 v[140:141], v[106:107], v[148:149], v[140:141]
	v_lshlrev_b32_e32 v162, 16, v80
	v_and_b32_e32 v163, 0xffff0000, v80
	v_pk_add_f32 v[94:95], v[94:95], 1.0 op_sel_hi:[1,0]
	v_pk_fma_f32 v[150:151], v[86:87], v[150:151], v[164:165]
	v_rcp_f32_e32 v94, v94
	v_rcp_f32_e32 v95, v95
	v_pk_fma_f32 v[86:87], v[86:87], v[132:133], v[90:91]
	v_pk_fma_f32 v[140:141], v[110:111], v[154:155], v[140:141]
	v_pk_mul_f32 v[160:161], v[104:105], v[120:121]
	v_pk_mul_f32 v[88:89], v[88:89], v[94:95]
	v_pk_mul_f32 v[94:95], v[104:105], v[146:147]
	v_pk_fma_f32 v[86:87], v[98:99], v[162:163], v[86:87]
	v_lshlrev_b32_e32 v90, 16, v84
	v_and_b32_e32 v91, 0xffff0000, v84
	v_pk_mul_f32 v[156:157], v[140:141], s[14:15] op_sel_hi:[1,0]
	v_lshlrev_b32_e32 v158, 16, v79
	v_and_b32_e32 v159, 0xffff0000, v79
	v_pk_fma_f32 v[142:143], v[96:97], v[142:143], v[160:161]
	v_pk_fma_f32 v[94:95], v[96:97], v[120:121], v[94:95]
	v_pk_fma_f32 v[86:87], v[114:115], v[90:91], v[86:87]
	v_exp_f32_e32 v156, v156
	v_exp_f32_e32 v157, v157
	v_pk_fma_f32 v[142:143], v[108:109], v[146:147], v[142:143]
	v_pk_fma_f32 v[94:95], v[108:109], v[158:159], v[94:95]
	v_lshlrev_b32_e32 v96, 16, v83
	v_and_b32_e32 v97, 0xffff0000, v83
	v_pk_mul_f32 v[90:91], v[86:87], s[14:15] op_sel_hi:[1,0]
	v_pk_fma_f32 v[142:143], v[112:113], v[158:159], v[142:143]
	v_pk_fma_f32 v[94:95], v[112:113], v[96:97], v[94:95]
	v_exp_f32_e32 v90, v90
	v_exp_f32_e32 v91, v91
	v_pk_mul_f32 v[160:161], v[142:143], s[14:15] op_sel_hi:[1,0]
	v_pk_mul_f32 v[96:97], v[94:95], s[14:15] op_sel_hi:[1,0]
	v_exp_f32_e32 v160, v160
	v_exp_f32_e32 v161, v161
	v_pk_fma_f32 v[150:151], v[98:99], v[144:145], v[150:151]
	v_exp_f32_e32 v96, v96
	v_exp_f32_e32 v97, v97
	v_pk_add_f32 v[156:157], v[156:157], 1.0 op_sel_hi:[1,0]
	v_pk_fma_f32 v[150:151], v[114:115], v[162:163], v[150:151]
	v_rcp_f32_e32 v156, v156
	v_rcp_f32_e32 v157, v157
	v_pk_mul_f32 v[164:165], v[150:151], s[14:15] op_sel_hi:[1,0]
	v_pk_add_f32 v[90:91], v[90:91], 1.0 op_sel_hi:[1,0]
	v_exp_f32_e32 v164, v164
	v_exp_f32_e32 v165, v165
	v_pk_fma_f32 v[152:153], v[100:101], v[168:169], v[152:153]
	v_rcp_f32_e32 v90, v90
	v_rcp_f32_e32 v91, v91
	v_pk_add_f32 v[160:161], v[160:161], 1.0 op_sel_hi:[1,0]
	v_pk_fma_f32 v[152:153], v[116:117], v[166:167], v[152:153]
	v_pk_add_f32 v[96:97], v[96:97], 1.0 op_sel_hi:[1,0]
	v_rcp_f32_e32 v160, v160
	v_rcp_f32_e32 v161, v161
	v_pk_mul_f32 v[170:171], v[152:153], s[14:15] op_sel_hi:[1,0]
	v_rcp_f32_e32 v96, v96
	v_rcp_f32_e32 v97, v97
	v_exp_f32_e32 v170, v170
	v_exp_f32_e32 v171, v171
	v_pk_mul_f32 v[140:141], v[140:141], v[156:157]
	v_pk_add_f32 v[164:165], v[164:165], 1.0 op_sel_hi:[1,0]
	v_bfe_u32 v156, v140, 16, 1
	v_pk_mul_f32 v[90:91], v[86:87], v[90:91]
	v_bfe_u32 v86, v88, 16, 1
	v_rcp_f32_e32 v164, v164
	v_rcp_f32_e32 v165, v165
	v_add3_u32 v140, v140, v156, s33
	v_bfe_u32 v156, v141, 16, 1
	v_add3_u32 v86, v88, v86, s33
	v_bfe_u32 v87, v89, 16, 1
	v_pk_mul_f32 v[142:143], v[142:143], v[160:161]
	v_lshrrev_b32_e32 v140, 16, v140
	v_add3_u32 v141, v141, v156, s33
	v_pk_mul_f32 v[94:95], v[94:95], v[96:97]
	v_lshrrev_b32_e32 v86, 16, v86
	v_add3_u32 v87, v89, v87, s33
	v_pk_add_f32 v[170:171], v[170:171], 1.0 op_sel_hi:[1,0]
	v_and_or_b32 v140, v141, s21, v140
	v_bfe_u32 v141, v142, 16, 1
	v_and_or_b32 v86, v87, s21, v86
	v_bfe_u32 v87, v94, 16, 1
	v_rcp_f32_e32 v170, v170
	v_rcp_f32_e32 v171, v171
	v_add3_u32 v141, v142, v141, s33
	v_bfe_u32 v142, v143, 16, 1
	v_add3_u32 v87, v94, v87, s33
	v_bfe_u32 v88, v95, 16, 1
	v_pk_mul_f32 v[150:151], v[150:151], v[164:165]
	v_lshrrev_b32_e32 v141, 16, v141
	v_add3_u32 v142, v143, v142, s33
	v_lshrrev_b32_e32 v87, 16, v87
	v_add3_u32 v88, v95, v88, s33
	v_and_or_b32 v141, v142, s21, v141
	v_bfe_u32 v142, v150, 16, 1
	v_and_or_b32 v87, v88, s21, v87
	v_bfe_u32 v88, v90, 16, 1
	v_add3_u32 v142, v150, v142, s33
	v_bfe_u32 v143, v151, 16, 1
	v_add3_u32 v88, v90, v88, s33
	v_bfe_u32 v89, v91, 16, 1
	v_pk_mul_f32 v[152:153], v[152:153], v[170:171]
	v_lshrrev_b32_e32 v142, 16, v142
	v_add3_u32 v143, v151, v143, s33
	v_lshrrev_b32_e32 v88, 16, v88
	v_add3_u32 v89, v91, v89, s33
	v_and_or_b32 v142, v143, s21, v142
	v_bfe_u32 v143, v152, 16, 1
	v_and_or_b32 v88, v89, s21, v88
	v_bfe_u32 v89, v92, 16, 1
	v_add3_u32 v143, v152, v143, s33
	v_bfe_u32 v150, v153, 16, 1
	v_add3_u32 v89, v92, v89, s33
	v_bfe_u32 v90, v93, 16, 1
	v_lshrrev_b32_e32 v143, 16, v143
	v_add3_u32 v150, v153, v150, s33
	v_lshrrev_b32_e32 v89, 16, v89
	v_add3_u32 v90, v93, v90, s33
	v_and_or_b32 v143, v150, s21, v143
	v_and_or_b32 v89, v90, s21, v89
	ds_write_b128 v130, v[140:143] offset:1056
	ds_write_b128 v130, v[86:89] offset:1584
	s_add_i32 s30, s30, 1
	s_cmp_ge_i32 s30, s5
	s_cbranch_scc1 .LBB0_334
	v_readlane_b32 s4, v254, 54
	s_mul_i32 s2, s4, s37
	s_sub_i32 s2, s42, s2
	v_readlane_b32 s3, v254, 55
	s_add_i32 s3, s3, s2
	s_cmp_ge_u32 s2, s4
	s_cselect_b32 s2, s3, s2
	s_sub_i32 s3, s2, s4
	s_cmp_ge_u32 s2, s4
	s_cselect_b32 s2, s3, s2
	v_readlane_b32 s3, v252, 7
	s_mul_i32 s2, s2, s3
	v_readlane_b32 s3, v252, 0
	s_add_i32 s2, s2, s3
	s_ashr_i32 s3, s2, 6
	s_mul_hi_i32 s4, s3, 0x2aaaaaab
	s_lshr_b32 s5, s4, 31
	s_ashr_i32 s4, s4, 1
	s_add_i32 s4, s4, s5
	s_mul_i32 s5, s4, 12
	s_lshl_b32 s2, s2, 6
	s_sub_i32 s7, s3, s5
	s_lshl_b32 s4, s4, 12
	s_and_b32 s5, s2, 0xfc0
	s_or_b32 s4, s4, s5
	v_cmp_gt_i32_e64 s[2:3], s5, v176
	v_add_u32_e32 v4, s4, v174
	v_readlane_b32 s4, v255, 32
	v_readlane_b32 s5, v255, 33
	v_lshl_add_u32 v130, s7, 7, v177
	v_mov_b32_e32 v5, v131
	v_mov_b64_e32 v[2:3], s[4:5]
	v_mad_i64_i32 v[2:3], s[4:5], v4, s15, v[2:3]
	v_mov_b32_e32 v4, v131
	v_lshl_add_u64 v[78:79], v[130:131], 1, v[2:3]
	v_mov_b32_e32 v2, v131
	v_mov_b32_e32 v3, v131
	v_mov_b64_e32 v[8:9], v[4:5]
	v_mov_b64_e32 v[6:7], v[2:3]
	s_and_saveexec_b64 s[4:5], s[2:3]
	s_cbranch_execz .LBB0_317
	v_add_co_u32_e32 v6, vcc, 0xfffef000, v78
	s_nop 1
	v_addc_co_u32_e32 v7, vcc, -1, v79, vcc
	global_load_dwordx4 v[6:9], v[6:7], off offset:-1024

.LBB0_447:
	ds_read_b128 v[110:113], v164 offset:17408
	ds_read_b128 v[114:117], v164 offset:17472
	ds_read_b128 v[144:147], v164 offset:17536
	ds_read_b128 v[148:151], v164 offset:17600
	ds_read_b128 v[152:155], v164 offset:21760
	ds_read_b128 v[170:173], v164 offset:21824
	ds_read_b128 v[174:177], v164 offset:21888
	ds_read_b128 v[178:181], v164 offset:21952
	s_waitcnt lgkmcnt(7)
	v_mfma_f32_16x16x32_bf16 v[110:113], v[110:113], v[94:97], 0
	s_waitcnt lgkmcnt(6)
	v_mfma_f32_16x16x32_bf16 v[110:113], v[114:117], v[98:101], v[110:113]
	s_waitcnt lgkmcnt(5)
	v_mfma_f32_16x16x32_bf16 v[110:113], v[144:147], v[102:105], v[110:113]
	s_waitcnt lgkmcnt(4)
	v_mfma_f32_16x16x32_bf16 v[110:113], v[148:151], v[106:109], v[110:113]
	ds_read_b128 v[114:117], v164 offset:26112
	ds_read_b128 v[144:147], v164 offset:26176
	ds_read_b128 v[148:151], v164 offset:26240
	ds_read_b128 v[182:185], v164 offset:26304
	s_waitcnt lgkmcnt(7)
	v_mfma_f32_16x16x32_bf16 v[152:155], v[152:155], v[94:97], 0
	s_waitcnt lgkmcnt(6)
	v_mfma_f32_16x16x32_bf16 v[152:155], v[170:173], v[98:101], v[152:155]
	s_waitcnt lgkmcnt(5)
	v_mfma_f32_16x16x32_bf16 v[152:155], v[174:177], v[102:105], v[152:155]
	s_waitcnt lgkmcnt(4)
	v_mfma_f32_16x16x32_bf16 v[152:155], v[178:181], v[106:109], v[152:155]
	ds_read_b128 v[170:173], v164 offset:30464
	ds_read_b128 v[174:177], v164 offset:30528
	ds_read_b128 v[178:181], v164 offset:30592
	ds_read_b128 v[186:189], v164 offset:30656
	s_waitcnt lgkmcnt(7)
	v_mfma_f32_16x16x32_bf16 v[114:117], v[114:117], v[94:97], 0
	s_waitcnt lgkmcnt(6)
	v_mfma_f32_16x16x32_bf16 v[114:117], v[144:147], v[98:101], v[114:117]
	s_waitcnt lgkmcnt(5)
	v_mfma_f32_16x16x32_bf16 v[114:117], v[148:151], v[102:105], v[114:117]
	s_waitcnt lgkmcnt(4)
	v_mfma_f32_16x16x32_bf16 v[114:117], v[182:185], v[106:109], v[114:117]
	ds_read_b128 v[144:147], v164
	ds_read_b128 v[148:151], v164 offset:64
	ds_read_b128 v[182:185], v164 offset:128
	ds_read_b128 v[190:193], v164 offset:192
	s_waitcnt lgkmcnt(7)
	v_mfma_f32_16x16x32_bf16 v[170:173], v[170:173], v[94:97], 0
	s_waitcnt lgkmcnt(6)
	v_mfma_f32_16x16x32_bf16 v[170:173], v[174:177], v[98:101], v[170:173]
	s_waitcnt lgkmcnt(5)
	v_mfma_f32_16x16x32_bf16 v[170:173], v[178:181], v[102:105], v[170:173]
	s_waitcnt lgkmcnt(4)
	v_mfma_f32_16x16x32_bf16 v[170:173], v[186:189], v[106:109], v[170:173]
	ds_read_b128 v[174:177], v164 offset:4352
	ds_read_b128 v[178:181], v164 offset:4416
	ds_read_b128 v[186:189], v164 offset:4480
	ds_read_b128 v[194:197], v164 offset:4544
	v_add_u32_e32 v142, 0x400, v163
	ds_read2_b32 v[198:199], v163 offset1:132
	ds_read2_b32 v[200:201], v142 offset0:8 offset1:140
	s_waitcnt lgkmcnt(0)
	v_mfma_f32_16x16x32_bf16 v[144:147], v[144:147], v[94:97], v[198:201]
	v_mfma_f32_16x16x32_bf16 v[144:147], v[148:151], v[98:101], v[144:147]
	v_mfma_f32_16x16x32_bf16 v[144:147], v[182:185], v[102:105], v[144:147]
	v_mfma_f32_16x16x32_bf16 v[144:147], v[190:193], v[106:109], v[144:147]
	ds_read_b128 v[148:151], v164 offset:8704
	ds_read_b128 v[182:185], v164 offset:8768
	ds_read_b128 v[190:193], v164 offset:8832
	ds_read_b128 v[198:201], v164 offset:8896
	v_add_u32_e32 v142, 0x2000, v163
	ds_read2_b32 v[202:203], v142 offset0:64 offset1:196
	v_add_u32_e32 v142, 0x2400, v163
	ds_read2_b32 v[204:205], v142 offset0:72 offset1:204
	s_waitcnt lgkmcnt(0)
	v_mfma_f32_16x16x32_bf16 v[174:177], v[174:177], v[94:97], v[202:205]
	v_mfma_f32_16x16x32_bf16 v[174:177], v[178:181], v[98:101], v[174:177]
	v_mfma_f32_16x16x32_bf16 v[174:177], v[186:189], v[102:105], v[174:177]
	v_mfma_f32_16x16x32_bf16 v[174:177], v[194:197], v[106:109], v[174:177]
	ds_read_b128 v[178:181], v164 offset:13056
	ds_read_b128 v[186:189], v164 offset:13120
	ds_read_b128 v[194:197], v164 offset:13184
	ds_read_b128 v[202:205], v164 offset:13248
	v_add_u32_e32 v142, 0x4200, v163
	ds_read2_b32 v[206:207], v142 offset1:132
	v_add_u32_e32 v142, 0x4600, v163
	ds_read2_b32 v[208:209], v142 offset0:8 offset1:140
	s_waitcnt lgkmcnt(0)
	v_mfma_f32_16x16x32_bf16 v[148:151], v[148:151], v[94:97], v[206:209]
	v_mfma_f32_16x16x32_bf16 v[148:151], v[182:185], v[98:101], v[148:151]
	v_mfma_f32_16x16x32_bf16 v[148:151], v[190:193], v[102:105], v[148:151]
	v_mfma_f32_16x16x32_bf16 v[148:151], v[198:201], v[106:109], v[148:151]
	ds_read_b128 v[182:185], v165 offset:34816
	ds_read_b128 v[190:193], v165 offset:34880
	ds_read_b128 v[198:201], v165 offset:37120
	ds_read_b128 v[206:209], v165 offset:37184
	v_add_u32_e32 v142, 0x6200, v163
	ds_read2_b32 v[210:211], v142 offset0:64 offset1:196
	v_add_u32_e32 v142, 0x6600, v163
	ds_read2_b32 v[212:213], v142 offset0:72 offset1:204
	s_waitcnt lgkmcnt(0)
	v_mfma_f32_16x16x32_bf16 v[94:97], v[178:181], v[94:97], v[210:213]
	v_mfma_f32_16x16x32_bf16 v[94:97], v[186:189], v[98:101], v[94:97]
	v_mfma_f32_16x16x32_bf16 v[94:97], v[194:197], v[102:105], v[94:97]
	ds_read_b128 v[98:101], v165 offset:39424
	ds_read_b128 v[102:105], v165 offset:39488
	ds_read_b128 v[178:181], v165 offset:41728
	ds_read_b128 v[186:189], v165 offset:41792
	v_mfma_f32_16x16x32_bf16 v[94:97], v[202:205], v[106:109], v[94:97]
	v_cvt_pk_bf16_f32 v106, v144, v145
	v_cvt_pk_bf16_f32 v107, v146, v147
	v_cvt_pk_bf16_f32 v108, v174, v175
	v_cvt_pk_bf16_f32 v109, v176, v177
	v_cvt_pk_bf16_f32 v144, v148, v149
	v_cvt_pk_bf16_f32 v145, v150, v151
	v_mfma_f32_16x16x32_bf16 v[110:113], v[182:185], v[106:109], v[110:113]
	s_nop 0
	v_cvt_pk_bf16_f32 v146, v94, v95
	v_cvt_pk_bf16_f32 v147, v96, v97
	s_nop 1
	v_mfma_f32_16x16x32_bf16 v[94:97], v[190:193], v[144:147], v[110:113]
	v_mfma_f32_16x16x32_bf16 v[110:113], v[198:201], v[106:109], v[152:155]
	ds_read_b128 v[148:151], v165 offset:44032
	s_nop 1
	ds_read_b128 v[152:155], v165 offset:44096
	ds_read_b128 v[174:177], v165 offset:46336
	ds_read_b128 v[182:185], v165 offset:46400
	v_mfma_f32_16x16x32_bf16 v[110:113], v[206:209], v[144:147], v[110:113]
	s_waitcnt lgkmcnt(7)
	v_mfma_f32_16x16x32_bf16 v[98:101], v[98:101], v[106:109], v[114:117]
	s_waitcnt lgkmcnt(6)
	v_mfma_f32_16x16x32_bf16 v[98:101], v[102:105], v[144:147], v[98:101]
	s_waitcnt lgkmcnt(5)
	v_mfma_f32_16x16x32_bf16 v[102:105], v[178:181], v[106:109], v[170:173]
	s_waitcnt lgkmcnt(4)
	v_mfma_f32_16x16x32_bf16 v[102:105], v[186:189], v[144:147], v[102:105]
	ds_read_b128 v[114:117], v165 offset:48640
	ds_read_b128 v[170:173], v165 offset:48704
	ds_read_b128 v[178:181], v165 offset:50944
	ds_read_b128 v[186:189], v165 offset:51008
	v_pk_mul_f32 v[64:65], v[64:65], v[130:131] op_sel_hi:[1,0]
	v_pk_mul_f32 v[62:63], v[62:63], v[130:131] op_sel_hi:[1,0]
	v_pk_mul_f32 v[68:69], v[68:69], v[130:131] op_sel_hi:[1,0]
	v_pk_mul_f32 v[66:67], v[66:67], v[130:131] op_sel_hi:[1,0]
	s_waitcnt lgkmcnt(7)
	v_mfma_f32_16x16x32_bf16 v[62:65], v[148:151], v[106:109], v[62:65]
	v_mul_f32_e64 v76, v76, v130
	v_mul_f32_e64 v77, v77, v130
	v_pk_mul_f32 v[74:75], v[74:75], v[130:131] op_sel_hi:[1,0]
	v_pk_mul_f32 v[72:73], v[72:73], v[130:131] op_sel_hi:[1,0]
	s_waitcnt lgkmcnt(5)
	v_mfma_f32_16x16x32_bf16 v[66:69], v[174:177], v[106:109], v[66:69]
	v_mul_f32_e64 v70, v70, v130
	v_mul_f32_e64 v71, v71, v130
	v_pk_mul_f32 v[80:81], v[80:81], v[130:131] op_sel_hi:[1,0]
	v_pk_mul_f32 v[78:79], v[78:79], v[130:131] op_sel_hi:[1,0]
	v_mfma_f32_16x16x32_bf16 v[62:65], v[152:155], v[144:147], v[62:65]
	v_mul_f32_e64 v84, v84, v130
	v_mul_f32_e64 v85, v85, v130
	v_pk_mul_f32 v[82:83], v[82:83], v[130:131] op_sel_hi:[1,0]
	v_pk_mul_f32 v[88:89], v[88:89], v[130:131] op_sel_hi:[1,0]
	s_waitcnt lgkmcnt(4)
	v_mfma_f32_16x16x32_bf16 v[66:69], v[182:185], v[144:147], v[66:69]
	ds_read_b128 v[148:151], v165 offset:53248
	ds_read_b128 v[152:155], v165 offset:53312
	ds_read_b128 v[174:177], v165 offset:55552
	ds_read_b128 v[182:185], v165 offset:55616
	v_pk_mul_f32 v[86:87], v[86:87], v[130:131] op_sel_hi:[1,0]
	v_pk_mul_f32 v[92:93], v[92:93], v[130:131] op_sel_hi:[1,0]
	v_pk_mul_f32 v[90:91], v[90:91], v[130:131] op_sel_hi:[1,0]
	s_waitcnt lgkmcnt(7)
	v_mfma_f32_16x16x32_bf16 v[74:77], v[114:117], v[106:109], v[74:77]
	s_waitcnt lgkmcnt(5)
	v_mfma_f32_16x16x32_bf16 v[70:73], v[178:181], v[106:109], v[70:73]
	v_mfma_f32_16x16x32_bf16 v[74:77], v[170:173], v[144:147], v[74:77]
	s_waitcnt lgkmcnt(4)
	v_mfma_f32_16x16x32_bf16 v[70:73], v[186:189], v[144:147], v[70:73]
	ds_read_b128 v[114:117], v165 offset:57856
	ds_read_b128 v[170:173], v165 offset:57920
	ds_read_b128 v[178:181], v165 offset:60160
	ds_read_b128 v[186:189], v165 offset:60224
	s_waitcnt lgkmcnt(7)
	v_mfma_f32_16x16x32_bf16 v[78:81], v[148:151], v[106:109], v[78:81]
	s_waitcnt lgkmcnt(5)
	v_mfma_f32_16x16x32_bf16 v[82:85], v[174:177], v[106:109], v[82:85]
	v_mfma_f32_16x16x32_bf16 v[78:81], v[152:155], v[144:147], v[78:81]
	s_waitcnt lgkmcnt(4)
	v_mfma_f32_16x16x32_bf16 v[82:85], v[182:185], v[144:147], v[82:85]
	ds_write2_b32 v167, v94, v95 offset1:132
	v_add_u32_e32 v94, 0xf800, v166
	ds_write2_b32 v94, v96, v97 offset0:8 offset1:140
	v_add_u32_e32 v94, 0x2000, v167
	ds_write2_b32 v94, v110, v111 offset0:64 offset1:196
	v_add_u32_e32 v94, 0x2400, v167
	ds_write2_b32 v94, v112, v113 offset0:72 offset1:204
	v_add_u32_e32 v94, 0x4200, v167
	ds_write2_b32 v94, v98, v99 offset1:132
	v_add_u32_e32 v94, 0x4600, v167
	ds_write2_b32 v94, v100, v101 offset0:8 offset1:140
	v_add_u32_e32 v94, 0x6200, v167
	ds_write2_b32 v94, v102, v103 offset0:64 offset1:196
	v_add_u32_e32 v94, 0x6600, v167
	ds_write2_b32 v94, v104, v105 offset0:72 offset1:204
	s_waitcnt lgkmcnt(0)
	s_barrier
	ds_read_b128 v[110:113], v168 offset:62464
	ds_read_b128 v[102:105], v168 offset:62480
	ds_read_b128 v[98:101], v168 offset:62496
	ds_read_b128 v[94:97], v168 offset:62512
	s_waitcnt lgkmcnt(14)
	v_mfma_f32_16x16x32_bf16 v[86:89], v[114:117], v[106:109], v[86:89]
	v_lshlrev_b32_e32 v150, 16, v46
	v_lshlrev_b32_e32 v151, 16, v47
	s_mov_b32 s30, 0x5f901000
	s_waitcnt lgkmcnt(13)
	v_mfma_f32_16x16x32_bf16 v[90:93], v[178:181], v[106:109], v[90:93]
	s_waitcnt lgkmcnt(3)
	v_pk_mul_f32 v[106:107], v[112:113], v[112:113]
	v_pk_mul_f32 v[108:109], v[110:111], v[110:111]
	s_nop 0
	v_pk_mov_b32 v[114:115], v[108:109], v[106:107] op_sel:[1,0]
	v_mov_b32_e32 v109, v107
	v_pk_add_f32 v[106:107], v[114:115], v[108:109]
	s_waitcnt lgkmcnt(2)
	v_pk_mul_f32 v[108:109], v[104:105], v[104:105]
	v_pk_mul_f32 v[114:115], v[102:103], v[102:103]
	v_pk_add_f32 v[106:107], v[106:107], v[106:107] op_sel:[0,1] op_sel_hi:[1,0]
	v_pk_mov_b32 v[116:117], v[114:115], v[108:109] op_sel:[1,0]
	v_mov_b32_e32 v115, v109
	v_pk_add_f32 v[108:109], v[116:117], v[114:115]
	s_waitcnt lgkmcnt(0)
	v_mul_f32_e32 v114, v94, v94
	v_mul_f32_e32 v115, v95, v95
	v_pk_add_f32 v[108:109], v[108:109], v[108:109] op_sel:[0,1] op_sel_hi:[1,0]
	v_mov_b32_e32 v107, v114
	v_mov_b32_e32 v109, v115
	v_pk_add_f32 v[106:107], v[106:107], v[108:109]
	v_mul_f32_e32 v108, v99, v99
	v_mul_f32_e32 v114, v101, v101
	v_mul_f32_e32 v116, v96, v96
	v_mul_f32_e32 v117, v97, v97
	v_pk_fma_f32 v[108:109], v[98:99], v[98:99], v[108:109] op_sel_hi:[1,1,0]
	v_pk_fma_f32 v[114:115], v[100:101], v[100:101], v[114:115] op_sel_hi:[1,1,0]
	v_mov_b32_e32 v109, v116
	v_mov_b32_e32 v115, v117
	v_pk_add_f32 v[108:109], v[108:109], v[114:115]
	v_mfma_f32_16x16x32_bf16 v[86:89], v[170:173], v[144:147], v[86:89]
	v_add_f32_e64 v106, v106, v108
	v_add_f32_e64 v107, v107, v109
	v_and_b32_e32 v108, 64, v235
	v_add_f32_e32 v106, v106, v107
	v_xor_b32_e32 v107, 1, v235
	v_add_u32_e32 v108, 64, v108
	v_cmp_lt_i32_e32 vcc, v107, v108
	v_mfma_f32_16x16x32_bf16 v[90:93], v[186:189], v[144:147], v[90:93]
	v_and_b32_e32 v146, 0xffff0000, v46
	v_cndmask_b32_e32 v107, v235, v107, vcc
	v_lshlrev_b32_e32 v107, 2, v107
	v_and_b32_e32 v147, 0xffff0000, v47
	v_lshl_add_u64 v[144:145], v[134:135], 0, s[6:7]
	s_waitcnt lgkmcnt(0)
	s_nop 1
	v_add_f32_dpp v106, v106, v106 quad_perm:[1,0,3,2] row_mask:0xf bank_mask:0xf
	v_xor_b32_e32 v107, 2, v235
	v_cmp_lt_i32_e32 vcc, v107, v108
	s_nop 1
	v_cndmask_b32_e32 v107, v235, v107, vcc
	v_lshlrev_b32_e32 v107, 2, v107
	s_waitcnt lgkmcnt(0)
	s_nop 1
	v_add_f32_dpp v106, v106, v106 quad_perm:[2,3,0,1] row_mask:0xf bank_mask:0xf
	v_xor_b32_e32 v107, 4, v235
	v_cmp_lt_i32_e32 vcc, v107, v108
	s_nop 1
	v_cndmask_b32_e32 v107, v235, v107, vcc
	v_lshlrev_b32_e32 v107, 2, v107
	s_waitcnt lgkmcnt(0)
	s_nop 1
	v_add_f32_dpp v106, v106, v106 row_half_mirror row_mask:0xf bank_mask:0xf
	v_fmamk_f32 v106, v106, 0x3c000000, v1
	v_cmp_gt_f32_e32 vcc, s0, v106
	v_mul_f32_e32 v107, 0x4b800000, v106
	s_nop 0
	v_cndmask_b32_e32 v106, v106, v107, vcc
	v_rsq_f32_e32 v106, v106
	s_nop 0
	v_mul_f32_e32 v107, 0x45800000, v106
	v_cndmask_b32_e32 v142, v106, v107, vcc
	v_mul_f32_e32 v106, 0xbfb8aa3b, v150
	v_exp_f32_e32 v106, v106
	v_mov_b32_e32 v107, v112
	v_mov_b32_e32 v112, v111
	v_add_f32_e32 v106, 1.0, v106
	v_rcp_f32_e32 v152, v106
	v_mul_f32_e32 v106, 0xbfb8aa3b, v146
	v_exp_f32_e32 v106, v106
	s_nop 0
	v_add_f32_e32 v106, 1.0, v106
	v_rcp_f32_e32 v148, v106
	v_mov_b32_e32 v106, v110
	v_pk_mul_f32 v[154:155], v[106:107], v[142:143] op_sel_hi:[1,0]
	v_mov_b32_e32 v106, v246
	v_mov_b32_e32 v107, v247
	v_mov_b32_e32 v108, v248
	v_mov_b32_e32 v109, v249
	v_mov_b32_e32 v114, v242
	v_mov_b32_e32 v115, v243
	v_mov_b32_e32 v116, v244
	v_mov_b32_e32 v117, v245
	v_mul_f32_e32 v110, 0xbfb8aa3b, v151
	v_exp_f32_e32 v110, v110
	v_mov_b32_e32 v171, v116
	v_add_f32_e32 v110, 1.0, v110
	v_rcp_f32_e32 v153, v110
	v_pk_mul_f32 v[110:111], v[112:113], v[142:143] op_sel_hi:[1,0]
	v_mul_f32_e32 v112, 0xbfb8aa3b, v147
	v_exp_f32_e32 v112, v112
	v_mov_b32_e32 v116, v115
	v_pk_mul_f32 v[110:111], v[116:117], v[110:111]
	v_mov_b32_e32 v170, v114
	v_add_f32_e32 v112, 1.0, v112
	v_rcp_f32_e32 v149, v112
	v_and_b32_e32 v114, 0xffff0000, v48
	v_mul_f32_e32 v117, 0xbfb8aa3b, v114
	v_exp_f32_e32 v117, v117
	v_pk_mul_f32 v[112:113], v[148:149], v[146:147]
	v_mov_b32_e32 v148, v102
	v_pk_mul_f32 v[110:111], v[112:113], v[110:111]
	v_lshlrev_b32_e32 v113, 16, v49
	v_mul_f32_e32 v102, 0xbfb8aa3b, v113
	v_exp_f32_e32 v102, v102
	v_and_b32_e32 v115, 0xffff0000, v49
	v_add_f32_e32 v117, 1.0, v117
	v_mov_b32_e32 v149, v104
	v_add_f32_e32 v102, 1.0, v102
	v_mov_b32_e32 v104, v103
	v_lshlrev_b32_e32 v112, 16, v48
	v_rcp_f32_e32 v146, v117
	v_rcp_f32_e32 v117, v102
	v_pk_mul_f32 v[102:103], v[104:105], v[142:143] op_sel_hi:[1,0]
	v_mul_f32_e32 v104, 0xbfb8aa3b, v115
	v_mul_f32_e32 v116, 0xbfb8aa3b, v112
	v_exp_f32_e32 v104, v104
	v_exp_f32_e32 v116, v116
	v_pk_mul_f32 v[150:151], v[152:153], v[150:151]
	v_mov_b32_e32 v153, v108
	v_add_f32_e32 v104, 1.0, v104
	v_add_f32_e32 v116, 1.0, v116
	v_rcp_f32_e32 v147, v104
	v_rcp_f32_e32 v116, v116
	v_mov_b32_e32 v108, v107
	v_pk_mul_f32 v[148:149], v[148:149], v[142:143] op_sel_hi:[1,0]
	v_mov_b32_e32 v152, v106
	v_pk_mul_f32 v[102:103], v[108:109], v[102:103]
	v_pk_mul_f32 v[104:105], v[146:147], v[114:115]
	v_pk_mul_f32 v[154:155], v[170:171], v[154:155]
	v_pk_mul_f32 v[148:149], v[152:153], v[148:149]
	v_pk_mul_f32 v[112:113], v[116:117], v[112:113]
	v_pk_mul_f32 v[102:103], v[104:105], v[102:103]
	v_pk_mul_f32 v[150:151], v[150:151], v[154:155]
	v_pk_mul_f32 v[112:113], v[112:113], v[148:149]
	v_bfe_u32 v105, v102, 16, 1
	v_bfe_u32 v104, v103, 16, 1
	v_add3_u32 v102, v102, v105, s33
	v_bfe_u32 v105, v151, 16, 1
	v_bfe_u32 v109, v113, 16, 1
	v_bfe_u32 v106, v111, 16, 1
	v_add3_u32 v103, v103, v104, s33
	v_bfe_u32 v104, v150, 16, 1
	v_bfe_u32 v108, v112, 16, 1
	v_add3_u32 v109, v113, v109, s33
	v_add3_u32 v105, v151, v105, s33
	v_bfe_u32 v107, v110, 16, 1
	v_add3_u32 v106, v111, v106, s33
	v_add3_u32 v108, v112, v108, s33
	v_add3_u32 v104, v150, v104, s33
	v_lshrrev_b32_e32 v111, 16, v105
	v_lshrrev_b32_e32 v105, 16, v109
	v_add3_u32 v107, v110, v107, s33
	v_lshrrev_b32_e32 v110, 16, v104
	v_lshrrev_b32_e32 v104, 16, v108
	v_and_or_b32 v105, v103, s21, v105
	v_and_or_b32 v103, v106, s21, v111
	v_add_co_u32_e32 v106, vcc, s30, v144
	v_and_or_b32 v104, v102, s21, v104
	v_and_or_b32 v102, v107, s21, v110
	v_addc_co_u32_e32 v107, vcc, 0, v145, vcc
	v_lshlrev_b32_e32 v114, 16, v50
	global_store_dwordx4 v[106:107], v[102:105], off offset:1024
	v_and_b32_e32 v108, 0xffff0000, v50
	v_lshlrev_b32_e32 v115, 16, v51
	v_mul_f32_e32 v102, 0xbfb8aa3b, v114
	v_exp_f32_e32 v102, v102
	v_mov_b32_e32 v103, v100
	v_and_b32_e32 v109, 0xffff0000, v51
	v_mov_b32_e32 v100, v99
	v_add_f32_e32 v102, 1.0, v102
	v_rcp_f32_e32 v116, v102
	v_mul_f32_e32 v102, 0xbfb8aa3b, v108
	v_exp_f32_e32 v102, v102
	s_andn2_b64 vcc, exec, s[8:9]
	v_add_f32_e32 v102, 1.0, v102
	v_rcp_f32_e32 v144, v102
	v_mov_b32_e32 v102, v98
	v_pk_mul_f32 v[146:147], v[102:103], v[142:143] op_sel_hi:[1,0]
	v_mov_b32_e32 v102, v230
	v_mov_b32_e32 v103, v234
	v_mov_b32_e32 v104, v236
	v_mov_b32_e32 v105, v238
	v_mov_b32_e32 v110, v250
	v_mov_b32_e32 v111, v251
	v_mov_b32_e32 v112, v241
	v_mov_b32_e32 v113, v228
	v_mul_f32_e32 v98, 0xbfb8aa3b, v115
	v_exp_f32_e32 v98, v98
	v_mov_b32_e32 v149, v112
	v_add_f32_e32 v98, 1.0, v98
	v_rcp_f32_e32 v117, v98
	v_pk_mul_f32 v[98:99], v[100:101], v[142:143] op_sel_hi:[1,0]
	v_mul_f32_e32 v100, 0xbfb8aa3b, v109
	v_exp_f32_e32 v100, v100
	v_mov_b32_e32 v112, v111
	v_pk_mul_f32 v[98:99], v[112:113], v[98:99]
	v_pk_mul_f32 v[114:115], v[116:117], v[114:115]
	v_add_f32_e32 v100, 1.0, v100
	v_rcp_f32_e32 v145, v100
	v_mov_b32_e32 v116, v94
	v_mov_b32_e32 v117, v96
	v_mov_b32_e32 v96, v95
	v_pk_mul_f32 v[100:101], v[144:145], v[108:109]
	v_and_b32_e32 v108, 0xffff0000, v52
	v_pk_mul_f32 v[98:99], v[100:101], v[98:99]
	v_lshlrev_b32_e32 v101, 16, v53
	v_mul_f32_e32 v111, 0xbfb8aa3b, v108
	v_mul_f32_e32 v94, 0xbfb8aa3b, v101
	v_exp_f32_e32 v111, v111
	v_exp_f32_e32 v94, v94
	v_and_b32_e32 v109, 0xffff0000, v53
	v_lshlrev_b32_e32 v100, 16, v52
	v_add_f32_e32 v111, 1.0, v111
	v_add_f32_e32 v94, 1.0, v94
	v_rcp_f32_e32 v112, v111
	v_rcp_f32_e32 v111, v94
	v_pk_mul_f32 v[94:95], v[96:97], v[142:143] op_sel_hi:[1,0]
	v_mul_f32_e32 v96, 0xbfb8aa3b, v109
	v_mov_b32_e32 v148, v110
	v_mul_f32_e32 v110, 0xbfb8aa3b, v100
	v_exp_f32_e32 v96, v96
	v_exp_f32_e32 v110, v110
	v_mov_b32_e32 v145, v104
	v_mov_b32_e32 v104, v103
	v_add_f32_e32 v96, 1.0, v96
	v_add_f32_e32 v110, 1.0, v110
	v_rcp_f32_e32 v113, v96
	v_rcp_f32_e32 v110, v110
	v_pk_mul_f32 v[116:117], v[116:117], v[142:143] op_sel_hi:[1,0]
	v_mov_b32_e32 v144, v102
	v_pk_mul_f32 v[94:95], v[94:95], v[104:105]
	v_pk_mul_f32 v[96:97], v[112:113], v[108:109]
	v_pk_mul_f32 v[146:147], v[148:149], v[146:147]
	v_pk_mul_f32 v[116:117], v[116:117], v[144:145]
	v_pk_mul_f32 v[100:101], v[110:111], v[100:101]
	v_pk_mul_f32 v[94:95], v[96:97], v[94:95]
	v_pk_mul_f32 v[114:115], v[114:115], v[146:147]
	v_pk_mul_f32 v[100:101], v[100:101], v[116:117]
	v_bfe_u32 v96, v95, 16, 1
	v_bfe_u32 v97, v94, 16, 1
	v_bfe_u32 v102, v99, 16, 1
	v_bfe_u32 v103, v98, 16, 1
	v_add3_u32 v98, v98, v103, s33
	v_add3_u32 v99, v99, v102, s33
	v_add3_u32 v94, v94, v97, s33
	v_add3_u32 v95, v95, v96, s33
	v_bfe_u32 v96, v114, 16, 1
	v_bfe_u32 v97, v115, 16, 1
	v_bfe_u32 v102, v100, 16, 1
	v_bfe_u32 v103, v101, 16, 1
	v_add3_u32 v101, v101, v103, s33
	v_add3_u32 v100, v100, v102, s33
	v_add3_u32 v97, v115, v97, s33
	v_add3_u32 v96, v114, v96, s33
	v_lshrrev_b32_e32 v102, 16, v96
	v_lshrrev_b32_e32 v103, 16, v97
	v_lshrrev_b32_e32 v96, 16, v100
	v_lshrrev_b32_e32 v97, 16, v101
	v_and_or_b32 v97, v95, s21, v97
	v_and_or_b32 v96, v94, s21, v96
	v_and_or_b32 v95, v99, s21, v103
	v_and_or_b32 v94, v98, s21, v102
	global_store_dwordx4 v[106:107], v[94:97], off offset:1040
	s_cbranch_vccnz .LBB0_444
	s_waitcnt vmcnt(2)
	v_mov_b64_e32 v[46:47], v[58:59]
	v_mov_b64_e32 v[50:51], v[54:55]
	v_mov_b64_e32 v[48:49], v[60:61]
	v_mov_b64_e32 v[52:53], v[56:57]
	v_mov_b32_e32 v130, v162
	ds_write_b128 v119, v[2:5]
	ds_write_b128 v156, v[6:9]
	ds_write_b128 v119, v[10:13] offset:17408
	ds_write_b128 v156, v[14:17] offset:17408
	ds_write_b128 v143, v[18:21] offset:34816
	ds_write_b128 v143, v[22:25] offset:44032
	ds_write_b128 v157, v[26:29] offset:44032
	ds_write_b128 v158, v[30:33]
	ds_write_b128 v159, v[34:37]
	ds_write_b128 v160, v[38:41]
	ds_write_b128 v161, v[42:45]
	s_branch .LBB0_444
